# code placement: every 32-MFMA mainloop segment padded (loader side) to start 8-byte aligned
# baseline (speedup 1.0000x reference)
; #define PG8_STAGE(bufoff, gbase, voff) do { _Pragma("unroll") for (int _i = 0; _i < 2; ++_i) \
;         __builtin_amdgcn_global_load_lds((const unsigned*)((const char*)(gbase) + (voff)[_i]), (LAS unsigned*)(lds + (bufoff) + ldsw + _i * 8192), 16, 0, 0); } while (0)
; #define PG8_LDA(dst, b, h) do { _Pragma("unroll") for (int m = 0; m < 4; ++m) _Pragma("unroll") for (int k = 0; k < 2; ++k) dst[m][k] = *(const LAS bf16x8*)(lds + PG8_SA(b, h) + aoff + m * 2048 + k * 1024); } while (0)
; #define PG8_LDB(dst, b, h) do { _Pragma("unroll") for (int n = 0; n < 2; ++n) _Pragma("unroll") for (int k = 0; k < 2; ++k) dst[n][k] = *(const LAS bf16x8*)(lds + PG8_SB(b, h) + boff + n * 2048 + k * 1024); } while (0)
; #define PG8_MMA(ai, bj, At, Bt) do { __builtin_amdgcn_s_setprio(1); _Pragma("unroll") for (int m = 0; m < 4; ++m) _Pragma("unroll") for (int n = 0; n < 2; ++n) _Pragma("unroll") for (int k = 0; k < 2; ++k) \
;         acc[ai][bj][m][n] = __builtin_amdgcn_mfma_f32_16x16x32_bf16(Bt[n][k], At[m][k], acc[ai][bj][m][n], 0, 0, 0); __builtin_amdgcn_s_setprio(0); } while (0)
; #define PG8_WAIT_V(n) asm volatile("s_waitcnt vmcnt(" #n ")" ::: "memory")
; #define PG8_WAIT_L(n) asm volatile("s_waitcnt lgkmcnt(" #n ")" ::: "memory")
; #define PG8_BAR __builtin_amdgcn_s_barrier()
; #define PG8_SCHED __builtin_amdgcn_sched_barrier(0)
; template <class Epi, bool ALIGN_EPI, bool SP2 = PG8_SP2_DEFAULT>
; __device__ __forceinline__ void gemm_phase(LAS unsigned char* lds, const Gemm g, const StaticOrder& S, const Epi& E) {
;     ...
;             PG8_LDB(B0, 0, 0); PG8_LDB(B1, 0, 1); PG8_SCHED; PG8_LDA(At, 0, 0); PG8_STAGE(PG8_SA(1, 1), a1 + hstepA, voffA);
;             PG8_WAIT_V(8); PG8_WAIT_L(0); PG8_BAR; PG8_MMA(0, 0, At, B0); PG8_MMA(0, 1, At, B1); PG8_BAR; PG8_SCHED;
;             PG8_LDA(At, 0, 1); PG8_STAGE(PG8_SB(0, 0), b2, voffB); PG8_STAGE(PG8_SB(0, 1), b2 + hstepB, voffB); PG8_STAGE(PG8_SA(0, 0), a2, voffA);
.LBB0_250:
	ds_read_b128 v[150:153], v147
	ds_read_b128 v[154:157], v147 offset:1024
	ds_read_b128 v[158:161], v147 offset:2048
	ds_read_b128 v[162:165], v147 offset:3072
	ds_read_b128 v[166:169], v148
	ds_read_b128 v[170:173], v148 offset:1024
	ds_read_b128 v[174:177], v148 offset:2048
	ds_read_b128 v[178:181], v148 offset:3072
	s_add_u32 s20, s18, 0xfff00080
	s_addc_u32 s21, s19, -1
	s_cmp_eq_u32 s44, 60
	s_cselect_b32 s23, s13, s21
	s_cselect_b32 s22, s40, s20
	s_cselect_b32 s21, s11, s43
	s_cselect_b32 s20, s41, s42
	v_lshl_add_u64 v[206:207], s[18:19], 0, v[136:137]
	s_add_i32 m0, s9, 0xc000
	ds_read_b128 v[182:185], v149
	ds_read_b128 v[186:189], v149 offset:1024
	ds_read_b128 v[190:193], v149 offset:2048
	ds_read_b128 v[198:201], v149 offset:3072
	ds_read_b128 v[202:205], v149 offset:4096
	ds_read_b128 v[216:219], v149 offset:5120
	ds_read_b128 v[220:223], v149 offset:6144
	ds_read_b128 v[224:227], v149 offset:7168
	global_load_lds_dwordx4 v[206:207], off
	v_lshl_add_u64 v[206:207], s[18:19], 0, v[138:139]
	s_add_i32 m0, s9, 0xe000
	s_nop 0
	global_load_lds_dwordx4 v[206:207], off
	s_nop 0
	s_waitcnt vmcnt(8)
	s_waitcnt lgkmcnt(0)
	s_barrier
	v_mfma_f32_16x16x32_bf16 v[124:127], v[150:153], v[182:185], v[124:127]
	v_mfma_f32_16x16x32_bf16 v[120:123], v[158:161], v[182:185], v[120:123]
	v_mfma_f32_16x16x32_bf16 v[116:119], v[150:153], v[190:193], v[116:119]
	v_mfma_f32_16x16x32_bf16 v[112:115], v[158:161], v[190:193], v[112:115]
	v_mfma_f32_16x16x32_bf16 v[100:103], v[150:153], v[202:205], v[100:103]
	v_mfma_f32_16x16x32_bf16 v[96:99], v[158:161], v[202:205], v[96:99]
	v_mfma_f32_16x16x32_bf16 v[84:87], v[150:153], v[220:223], v[84:87]
	v_mfma_f32_16x16x32_bf16 v[80:83], v[158:161], v[220:223], v[80:83]
	v_mfma_f32_16x16x32_bf16 v[124:127], v[154:157], v[186:189], v[124:127]
	v_mfma_f32_16x16x32_bf16 v[120:123], v[162:165], v[186:189], v[120:123]
	v_mfma_f32_16x16x32_bf16 v[116:119], v[154:157], v[198:201], v[116:119]
	v_mfma_f32_16x16x32_bf16 v[112:115], v[162:165], v[198:201], v[112:115]
	v_mfma_f32_16x16x32_bf16 v[100:103], v[154:157], v[216:219], v[100:103]
	v_mfma_f32_16x16x32_bf16 v[96:99], v[162:165], v[216:219], v[96:99]
	v_mfma_f32_16x16x32_bf16 v[84:87], v[154:157], v[224:227], v[84:87]
	v_mfma_f32_16x16x32_bf16 v[80:83], v[162:165], v[224:227], v[80:83]
	v_mfma_f32_16x16x32_bf16 v[108:111], v[166:169], v[182:185], v[108:111]
	v_mfma_f32_16x16x32_bf16 v[104:107], v[174:177], v[182:185], v[104:107]
	v_mfma_f32_16x16x32_bf16 v[92:95], v[166:169], v[190:193], v[92:95]
	v_mfma_f32_16x16x32_bf16 v[88:91], v[174:177], v[190:193], v[88:91]
	v_mfma_f32_16x16x32_bf16 v[76:79], v[166:169], v[202:205], v[76:79]
	v_mfma_f32_16x16x32_bf16 v[72:75], v[174:177], v[202:205], v[72:75]
	v_mfma_f32_16x16x32_bf16 v[68:71], v[166:169], v[220:223], v[68:71]
	v_mfma_f32_16x16x32_bf16 v[64:67], v[174:177], v[220:223], v[64:67]
	v_mfma_f32_16x16x32_bf16 v[108:111], v[170:173], v[186:189], v[108:111]
	v_mfma_f32_16x16x32_bf16 v[104:107], v[178:181], v[186:189], v[104:107]
	v_mfma_f32_16x16x32_bf16 v[92:95], v[170:173], v[198:201], v[92:95]
	v_mfma_f32_16x16x32_bf16 v[88:91], v[178:181], v[198:201], v[88:91]
	v_mfma_f32_16x16x32_bf16 v[76:79], v[170:173], v[216:219], v[76:79]
	v_mfma_f32_16x16x32_bf16 v[72:75], v[178:181], v[216:219], v[72:75]
	v_mfma_f32_16x16x32_bf16 v[68:71], v[170:173], v[224:227], v[68:71]
	v_mfma_f32_16x16x32_bf16 v[64:67], v[178:181], v[224:227], v[64:67]
	s_barrier
	s_add_i32 s45, s36, s24
	v_lshl_add_u64 v[206:207], s[20:21], 0, v[132:133]
	s_mov_b32 m0, s45
	ds_read_b128 v[182:185], v149 offset:16384
	ds_read_b128 v[186:189], v149 offset:17408
	ds_read_b128 v[190:193], v149 offset:18432
	ds_read_b128 v[198:201], v149 offset:19456
	ds_read_b128 v[202:205], v149 offset:20480
	ds_read_b128 v[216:219], v149 offset:21504
	ds_read_b128 v[220:223], v149 offset:22528
	ds_read_b128 v[224:227], v149 offset:23552
	global_load_lds_dwordx4 v[206:207], off
	s_add_i32 m0, s45, 0x2000
	s_add_u32 s46, s20, 0x100000
	v_lshl_add_u64 v[210:211], s[20:21], 0, v[128:129]
	s_addc_u32 s47, s21, 0
	s_add_i32 s45, s37, s24
	global_load_lds_dwordx4 v[210:211], off
	v_lshl_add_u64 v[228:229], s[46:47], 0, v[132:133]
	s_mov_b32 m0, s45
	v_lshl_add_u64 v[230:231], s[22:23], 0, v[130:131]
	global_load_lds_dwordx4 v[228:229], off
	v_lshl_add_u64 v[228:229], s[46:47], 0, v[128:129]
	s_add_i32 m0, s45, 0x2000
	s_nop 0
	global_load_lds_dwordx4 v[228:229], off
	v_lshl_add_u64 v[228:229], s[22:23], 0, v[134:135]
	s_mov_b32 m0, s9
	s_nop 0
	global_load_lds_dwordx4 v[228:229], off
	s_mov_b32 m0, s27
	s_nop 0
	global_load_lds_dwordx4 v[230:231], off
	s_waitcnt vmcnt(8)
	s_waitcnt lgkmcnt(0)
	s_barrier
; #define PG8_STAGE(bufoff, gbase, voff) do { _Pragma("unroll") for (int _i = 0; _i < 2; ++_i) \
;         __builtin_amdgcn_global_load_lds((const unsigned*)((const char*)(gbase) + (voff)[_i]), (LAS unsigned*)(lds + (bufoff) + ldsw + _i * 8192), 16, 0, 0); } while (0)
; #define PG8_LDA(dst, b, h) do { _Pragma("unroll") for (int m = 0; m < 4; ++m) _Pragma("unroll") for (int k = 0; k < 2; ++k) dst[m][k] = *(const LAS bf16x8*)(lds + PG8_SA(b, h) + aoff + m * 2048 + k * 1024); } while (0)
; #define PG8_LDB(dst, b, h) do { _Pragma("unroll") for (int n = 0; n < 2; ++n) _Pragma("unroll") for (int k = 0; k < 2; ++k) dst[n][k] = *(const LAS bf16x8*)(lds + PG8_SB(b, h) + boff + n * 2048 + k * 1024); } while (0)
; #define PG8_MMA(ai, bj, At, Bt) do { __builtin_amdgcn_s_setprio(1); _Pragma("unroll") for (int m = 0; m < 4; ++m) _Pragma("unroll") for (int n = 0; n < 2; ++n) _Pragma("unroll") for (int k = 0; k < 2; ++k) \
;         acc[ai][bj][m][n] = __builtin_amdgcn_mfma_f32_16x16x32_bf16(Bt[n][k], At[m][k], acc[ai][bj][m][n], 0, 0, 0); __builtin_amdgcn_s_setprio(0); } while (0)
; #define PG8_WAIT_V(n) asm volatile("s_waitcnt vmcnt(" #n ")" ::: "memory")
; #define PG8_WAIT_L(n) asm volatile("s_waitcnt lgkmcnt(" #n ")" ::: "memory")
; #define PG8_BAR __builtin_amdgcn_s_barrier()
; #define PG8_SCHED __builtin_amdgcn_sched_barrier(0)
; template <class Epi, bool ALIGN_EPI, bool SP2 = PG8_SP2_DEFAULT>
; __device__ __forceinline__ void gemm_phase(LAS unsigned char* lds, const Gemm g, const StaticOrder& S, const Epi& E) {
;     ...
;             PG8_WAIT_V(8); PG8_WAIT_L(0); PG8_BAR; PG8_MMA(1, 0, At, B0); PG8_MMA(1, 1, At, B1); PG8_BAR; PG8_SCHED;
;             PG8_LDB(B0, 1, 0); PG8_LDB(B1, 1, 1); PG8_SCHED; PG8_LDA(At, 1, 0); PG8_STAGE(PG8_SA(0, 1), a2 + hstepA, voffA);
;             PG8_WAIT_V(8); PG8_WAIT_L(0); PG8_BAR; PG8_MMA(0, 0, At, B0); PG8_MMA(0, 1, At, B1); PG8_BAR; PG8_SCHED;
	v_mfma_f32_16x16x32_bf16 v[60:63], v[150:153], v[182:185], v[60:63]
	v_mfma_f32_16x16x32_bf16 v[56:59], v[158:161], v[182:185], v[56:59]
	v_mfma_f32_16x16x32_bf16 v[52:55], v[150:153], v[190:193], v[52:55]
	v_mfma_f32_16x16x32_bf16 v[48:51], v[158:161], v[190:193], v[48:51]
	v_mfma_f32_16x16x32_bf16 v[36:39], v[150:153], v[202:205], v[36:39]
	v_mfma_f32_16x16x32_bf16 v[32:35], v[158:161], v[202:205], v[32:35]
	v_mfma_f32_16x16x32_bf16 v[20:23], v[150:153], v[220:223], v[20:23]
	v_mfma_f32_16x16x32_bf16 v[16:19], v[158:161], v[220:223], v[16:19]
	v_mfma_f32_16x16x32_bf16 v[60:63], v[154:157], v[186:189], v[60:63]
	v_mfma_f32_16x16x32_bf16 v[56:59], v[162:165], v[186:189], v[56:59]
	v_mfma_f32_16x16x32_bf16 v[52:55], v[154:157], v[198:201], v[52:55]
	v_mfma_f32_16x16x32_bf16 v[48:51], v[162:165], v[198:201], v[48:51]
	v_mfma_f32_16x16x32_bf16 v[36:39], v[154:157], v[216:219], v[36:39]
	v_mfma_f32_16x16x32_bf16 v[32:35], v[162:165], v[216:219], v[32:35]
	v_mfma_f32_16x16x32_bf16 v[20:23], v[154:157], v[224:227], v[20:23]
	v_mfma_f32_16x16x32_bf16 v[16:19], v[162:165], v[224:227], v[16:19]
	v_mfma_f32_16x16x32_bf16 v[44:47], v[166:169], v[182:185], v[44:47]
	v_mfma_f32_16x16x32_bf16 v[40:43], v[174:177], v[182:185], v[40:43]
	v_mfma_f32_16x16x32_bf16 v[28:31], v[166:169], v[190:193], v[28:31]
	v_mfma_f32_16x16x32_bf16 v[24:27], v[174:177], v[190:193], v[24:27]
	v_mfma_f32_16x16x32_bf16 v[12:15], v[166:169], v[202:205], v[12:15]
	v_mfma_f32_16x16x32_bf16 v[8:11], v[174:177], v[202:205], v[8:11]
	v_mfma_f32_16x16x32_bf16 v[4:7], v[166:169], v[220:223], v[4:7]
	v_mfma_f32_16x16x32_bf16 v[0:3], v[174:177], v[220:223], v[0:3]
	v_mfma_f32_16x16x32_bf16 v[44:47], v[170:173], v[186:189], v[44:47]
	v_mfma_f32_16x16x32_bf16 v[40:43], v[178:181], v[186:189], v[40:43]
	v_mfma_f32_16x16x32_bf16 v[28:31], v[170:173], v[198:201], v[28:31]
	v_mfma_f32_16x16x32_bf16 v[24:27], v[178:181], v[198:201], v[24:27]
	v_mfma_f32_16x16x32_bf16 v[12:15], v[170:173], v[216:219], v[12:15]
	v_mfma_f32_16x16x32_bf16 v[8:11], v[178:181], v[216:219], v[8:11]
	v_mfma_f32_16x16x32_bf16 v[4:7], v[170:173], v[224:227], v[4:7]
	v_mfma_f32_16x16x32_bf16 v[0:3], v[178:181], v[224:227], v[0:3]
	s_barrier
	s_add_i32 s45, 0, 0x18000
	s_add_i32 s46, 0, 0x1c000
	v_add_u32_e32 v162, s45, v145
	v_add_u32_e32 v178, s46, v145
	ds_read_b128 v[150:153], v162
	ds_read_b128 v[154:157], v162 offset:1024
	ds_read_b128 v[158:161], v162 offset:2048
	ds_read_b128 v[162:165], v162 offset:3072
	ds_read_b128 v[166:169], v178
	ds_read_b128 v[170:173], v178 offset:1024
	ds_read_b128 v[174:177], v178 offset:2048
	ds_read_b128 v[178:181], v178 offset:3072
	s_add_u32 s22, s22, 0x100000
	s_addc_u32 s23, s23, 0
	s_mov_b32 m0, s28
	v_lshl_add_u64 v[232:233], s[22:23], 0, v[134:135]
	ds_read_b128 v[182:185], v149 offset:32768
	ds_read_b128 v[186:189], v149 offset:33792
	ds_read_b128 v[190:193], v149 offset:34816
	ds_read_b128 v[198:201], v149 offset:35840
	ds_read_b128 v[202:205], v149 offset:36864
	ds_read_b128 v[216:219], v149 offset:37888
	ds_read_b128 v[220:223], v149 offset:38912
	ds_read_b128 v[224:227], v149 offset:39936
	global_load_lds_dwordx4 v[232:233], off
	v_lshl_add_u64 v[232:233], s[22:23], 0, v[130:131]
	s_mov_b32 m0, s29
	s_nop 0
	global_load_lds_dwordx4 v[232:233], off
	s_waitcnt vmcnt(8)
	s_waitcnt lgkmcnt(0)
	s_barrier
	v_mfma_f32_16x16x32_bf16 v[124:127], v[150:153], v[182:185], v[124:127]
	v_mfma_f32_16x16x32_bf16 v[120:123], v[158:161], v[182:185], v[120:123]
	v_mfma_f32_16x16x32_bf16 v[116:119], v[150:153], v[190:193], v[116:119]
	v_mfma_f32_16x16x32_bf16 v[112:115], v[158:161], v[190:193], v[112:115]
	v_mfma_f32_16x16x32_bf16 v[100:103], v[150:153], v[202:205], v[100:103]
	v_mfma_f32_16x16x32_bf16 v[96:99], v[158:161], v[202:205], v[96:99]
	v_mfma_f32_16x16x32_bf16 v[84:87], v[150:153], v[220:223], v[84:87]
	v_mfma_f32_16x16x32_bf16 v[80:83], v[158:161], v[220:223], v[80:83]
	v_mfma_f32_16x16x32_bf16 v[124:127], v[154:157], v[186:189], v[124:127]
	v_mfma_f32_16x16x32_bf16 v[120:123], v[162:165], v[186:189], v[120:123]
	v_mfma_f32_16x16x32_bf16 v[116:119], v[154:157], v[198:201], v[116:119]
	v_mfma_f32_16x16x32_bf16 v[112:115], v[162:165], v[198:201], v[112:115]
	v_mfma_f32_16x16x32_bf16 v[100:103], v[154:157], v[216:219], v[100:103]
	v_mfma_f32_16x16x32_bf16 v[96:99], v[162:165], v[216:219], v[96:99]
	v_mfma_f32_16x16x32_bf16 v[84:87], v[154:157], v[224:227], v[84:87]
	v_mfma_f32_16x16x32_bf16 v[80:83], v[162:165], v[224:227], v[80:83]
	v_mfma_f32_16x16x32_bf16 v[108:111], v[166:169], v[182:185], v[108:111]
	v_mfma_f32_16x16x32_bf16 v[104:107], v[174:177], v[182:185], v[104:107]
	v_mfma_f32_16x16x32_bf16 v[92:95], v[166:169], v[190:193], v[92:95]
	v_mfma_f32_16x16x32_bf16 v[88:91], v[174:177], v[190:193], v[88:91]
	v_mfma_f32_16x16x32_bf16 v[76:79], v[166:169], v[202:205], v[76:79]
	v_mfma_f32_16x16x32_bf16 v[72:75], v[174:177], v[202:205], v[72:75]
	v_mfma_f32_16x16x32_bf16 v[68:71], v[166:169], v[220:223], v[68:71]
	v_mfma_f32_16x16x32_bf16 v[64:67], v[174:177], v[220:223], v[64:67]
	v_mfma_f32_16x16x32_bf16 v[108:111], v[170:173], v[186:189], v[108:111]
	v_mfma_f32_16x16x32_bf16 v[104:107], v[178:181], v[186:189], v[104:107]
	v_mfma_f32_16x16x32_bf16 v[92:95], v[170:173], v[198:201], v[92:95]
	v_mfma_f32_16x16x32_bf16 v[88:91], v[178:181], v[198:201], v[88:91]
	v_mfma_f32_16x16x32_bf16 v[76:79], v[170:173], v[216:219], v[76:79]
	v_mfma_f32_16x16x32_bf16 v[72:75], v[178:181], v[216:219], v[72:75]
	v_mfma_f32_16x16x32_bf16 v[68:71], v[170:173], v[224:227], v[68:71]
	v_mfma_f32_16x16x32_bf16 v[64:67], v[178:181], v[224:227], v[64:67]
	s_barrier
; #define PG8_STAGE(bufoff, gbase, voff) do { _Pragma("unroll") for (int _i = 0; _i < 2; ++_i) \
;         __builtin_amdgcn_global_load_lds((const unsigned*)((const char*)(gbase) + (voff)[_i]), (LAS unsigned*)(lds + (bufoff) + ldsw + _i * 8192), 16, 0, 0); } while (0)
; #define PG8_LDA(dst, b, h) do { _Pragma("unroll") for (int m = 0; m < 4; ++m) _Pragma("unroll") for (int k = 0; k < 2; ++k) dst[m][k] = *(const LAS bf16x8*)(lds + PG8_SA(b, h) + aoff + m * 2048 + k * 1024); } while (0)
; #define PG8_MMA(ai, bj, At, Bt) do { __builtin_amdgcn_s_setprio(1); _Pragma("unroll") for (int m = 0; m < 4; ++m) _Pragma("unroll") for (int n = 0; n < 2; ++n) _Pragma("unroll") for (int k = 0; k < 2; ++k) \
;         acc[ai][bj][m][n] = __builtin_amdgcn_mfma_f32_16x16x32_bf16(Bt[n][k], At[m][k], acc[ai][bj][m][n], 0, 0, 0); __builtin_amdgcn_s_setprio(0); } while (0)
; #define PG8_WAIT_V(n) asm volatile("s_waitcnt vmcnt(" #n ")" ::: "memory")
; #define PG8_WAIT_L(n) asm volatile("s_waitcnt lgkmcnt(" #n ")" ::: "memory")
; #define PG8_BAR __builtin_amdgcn_s_barrier()
; #define PG8_SCHED __builtin_amdgcn_sched_barrier(0)
; template <class Epi, bool ALIGN_EPI, bool SP2 = PG8_SP2_DEFAULT>
; __device__ __forceinline__ void gemm_phase(LAS unsigned char* lds, const Gemm g, const StaticOrder& S, const Epi& E) {
;     ...
;             PG8_LDA(At, 1, 1); PG8_STAGE(PG8_SB(1, 0), b3, voffB); PG8_STAGE(PG8_SB(1, 1), b3 + hstepB, voffB); PG8_STAGE(PG8_SA(1, 0), a3, voffA);
;             PG8_WAIT_V(8); PG8_WAIT_L(0); PG8_BAR; PG8_MMA(1, 0, At, B0); PG8_MMA(1, 1, At, B1); PG8_BAR; PG8_SCHED;
;     ...
;         if constexpr (ALIGN_EPI) { if (wr == 0) PG8_BAR; }
	s_add_i32 s22, s45, s24
	v_lshl_add_u64 v[206:207], v[206:207], 0, s[4:5]
	s_mov_b32 m0, s22
	ds_read_b128 v[182:185], v149 offset:49152
	ds_read_b128 v[186:189], v149 offset:50176
	ds_read_b128 v[190:193], v149 offset:51200
	ds_read_b128 v[198:201], v149 offset:52224
	ds_read_b128 v[202:205], v149 offset:53248
	ds_read_b128 v[216:219], v149 offset:54272
	ds_read_b128 v[220:223], v149 offset:55296
	ds_read_b128 v[224:227], v149 offset:56320
	global_load_lds_dwordx4 v[206:207], off
	s_add_i32 m0, s22, 0x2000
	s_add_u32 s20, s20, 0x100080
	v_lshl_add_u64 v[206:207], v[210:211], 0, s[4:5]
	s_addc_u32 s21, s21, 0
	s_add_i32 s22, s46, s24
	global_load_lds_dwordx4 v[206:207], off
	v_lshl_add_u64 v[206:207], s[20:21], 0, v[132:133]
	s_mov_b32 m0, s22
	s_nop 0
	global_load_lds_dwordx4 v[206:207], off
	v_lshl_add_u64 v[206:207], s[20:21], 0, v[128:129]
	s_add_i32 m0, s22, 0x2000
	s_nop 0
	global_load_lds_dwordx4 v[206:207], off
	v_lshl_add_u64 v[206:207], v[228:229], 0, s[4:5]
	s_mov_b32 m0, s33
	s_nop 0
	global_load_lds_dwordx4 v[206:207], off
	v_lshl_add_u64 v[206:207], v[230:231], 0, s[4:5]
	s_mov_b32 m0, s34
	s_nop 0
	global_load_lds_dwordx4 v[206:207], off
	s_nop 0
	s_waitcnt vmcnt(8)
	s_waitcnt lgkmcnt(0)
	s_barrier
	v_mfma_f32_16x16x32_bf16 v[60:63], v[150:153], v[182:185], v[60:63]
	v_mfma_f32_16x16x32_bf16 v[56:59], v[158:161], v[182:185], v[56:59]
	v_mfma_f32_16x16x32_bf16 v[52:55], v[150:153], v[190:193], v[52:55]
	v_mfma_f32_16x16x32_bf16 v[48:51], v[158:161], v[190:193], v[48:51]
	v_mfma_f32_16x16x32_bf16 v[36:39], v[150:153], v[202:205], v[36:39]
	v_mfma_f32_16x16x32_bf16 v[32:35], v[158:161], v[202:205], v[32:35]
	v_mfma_f32_16x16x32_bf16 v[20:23], v[150:153], v[220:223], v[20:23]
	v_mfma_f32_16x16x32_bf16 v[16:19], v[158:161], v[220:223], v[16:19]
	v_mfma_f32_16x16x32_bf16 v[60:63], v[154:157], v[186:189], v[60:63]
	v_mfma_f32_16x16x32_bf16 v[56:59], v[162:165], v[186:189], v[56:59]
	v_mfma_f32_16x16x32_bf16 v[52:55], v[154:157], v[198:201], v[52:55]
	v_mfma_f32_16x16x32_bf16 v[48:51], v[162:165], v[198:201], v[48:51]
	v_mfma_f32_16x16x32_bf16 v[36:39], v[154:157], v[216:219], v[36:39]
	v_mfma_f32_16x16x32_bf16 v[32:35], v[162:165], v[216:219], v[32:35]
	v_mfma_f32_16x16x32_bf16 v[20:23], v[154:157], v[224:227], v[20:23]
	v_mfma_f32_16x16x32_bf16 v[16:19], v[162:165], v[224:227], v[16:19]
	v_mfma_f32_16x16x32_bf16 v[44:47], v[166:169], v[182:185], v[44:47]
	v_mfma_f32_16x16x32_bf16 v[40:43], v[174:177], v[182:185], v[40:43]
	v_mfma_f32_16x16x32_bf16 v[28:31], v[166:169], v[190:193], v[28:31]
	v_mfma_f32_16x16x32_bf16 v[24:27], v[174:177], v[190:193], v[24:27]
	v_mfma_f32_16x16x32_bf16 v[12:15], v[166:169], v[202:205], v[12:15]
	v_mfma_f32_16x16x32_bf16 v[8:11], v[174:177], v[202:205], v[8:11]
	v_mfma_f32_16x16x32_bf16 v[4:7], v[166:169], v[220:223], v[4:7]
	v_mfma_f32_16x16x32_bf16 v[0:3], v[174:177], v[220:223], v[0:3]
	v_mfma_f32_16x16x32_bf16 v[44:47], v[170:173], v[186:189], v[44:47]
	v_mfma_f32_16x16x32_bf16 v[40:43], v[178:181], v[186:189], v[40:43]
	v_mfma_f32_16x16x32_bf16 v[28:31], v[170:173], v[198:201], v[28:31]
	v_mfma_f32_16x16x32_bf16 v[24:27], v[178:181], v[198:201], v[24:27]
	v_mfma_f32_16x16x32_bf16 v[12:15], v[170:173], v[216:219], v[12:15]
	v_mfma_f32_16x16x32_bf16 v[8:11], v[178:181], v[216:219], v[8:11]
	v_mfma_f32_16x16x32_bf16 v[4:7], v[170:173], v[224:227], v[4:7]
	v_mfma_f32_16x16x32_bf16 v[0:3], v[178:181], v[224:227], v[0:3]
	s_barrier
	s_add_i32 s44, s44, 2
	s_add_u32 s18, s18, 0x100
	s_addc_u32 s19, s19, 0
	s_add_u32 s42, s42, 0x100
	s_addc_u32 s43, s43, 0
	s_cmp_gt_u32 s44, 61
	s_cbranch_scc0 .LBB0_250
	s_and_b64 vcc, exec, s[6:7]
	s_cbranch_vccz .LBB0_253
	s_barrier

; #define PG8_STAGE(bufoff, gbase, voff) do { _Pragma("unroll") for (int _i = 0; _i < 2; ++_i) \
;         __builtin_amdgcn_global_load_lds((const unsigned*)((const char*)(gbase) + (voff)[_i]), (LAS unsigned*)(lds + (bufoff) + ldsw + _i * 8192), 16, 0, 0); } while (0)
; #define PG8_LDA(dst, b, h) do { _Pragma("unroll") for (int m = 0; m < 4; ++m) _Pragma("unroll") for (int k = 0; k < 2; ++k) dst[m][k] = *(const LAS bf16x8*)(lds + PG8_SA(b, h) + aoff + m * 2048 + k * 1024); } while (0)
; #define PG8_LDB(dst, b, h) do { _Pragma("unroll") for (int n = 0; n < 2; ++n) _Pragma("unroll") for (int k = 0; k < 2; ++k) dst[n][k] = *(const LAS bf16x8*)(lds + PG8_SB(b, h) + boff + n * 2048 + k * 1024); } while (0)
; #define PG8_MMA(ai, bj, At, Bt) do { __builtin_amdgcn_s_setprio(1); _Pragma("unroll") for (int m = 0; m < 4; ++m) _Pragma("unroll") for (int n = 0; n < 2; ++n) _Pragma("unroll") for (int k = 0; k < 2; ++k) \
;         acc[ai][bj][m][n] = __builtin_amdgcn_mfma_f32_16x16x32_bf16(Bt[n][k], At[m][k], acc[ai][bj][m][n], 0, 0, 0); __builtin_amdgcn_s_setprio(0); } while (0)
; #define PG8_WAIT_V(n) asm volatile("s_waitcnt vmcnt(" #n ")" ::: "memory")
; #define PG8_WAIT_L(n) asm volatile("s_waitcnt lgkmcnt(" #n ")" ::: "memory")
; #define PG8_BAR __builtin_amdgcn_s_barrier()
; #define PG8_SCHED __builtin_amdgcn_sched_barrier(0)
; template <class Epi, bool ALIGN_EPI, bool SP2 = PG8_SP2_DEFAULT>
; __device__ __forceinline__ void gemm_phase(LAS unsigned char* lds, const Gemm g, const StaticOrder& S, const Epi& E) {
;     ...
;             PG8_LDB(B0, 0, 0); PG8_LDB(B1, 0, 1); PG8_SCHED; PG8_LDA(At, 0, 0); PG8_STAGE(PG8_SA(1, 1), a1 + hstepA, voffA);
;             PG8_WAIT_V(8); PG8_WAIT_L(0); PG8_BAR; PG8_MMA(0, 0, At, B0); PG8_MMA(0, 1, At, B1); PG8_BAR; PG8_SCHED;
;             PG8_LDA(At, 0, 1); PG8_STAGE(PG8_SB(0, 0), b2, voffB); PG8_STAGE(PG8_SB(0, 1), b2 + hstepB, voffB); PG8_STAGE(PG8_SA(0, 0), a2, voffA);
.LBB0_428:
	ds_read_b128 v[128:131], v165
	ds_read_b128 v[132:135], v165 offset:1024
	ds_read_b128 v[136:139], v165 offset:2048
	ds_read_b128 v[140:143], v165 offset:3072
	ds_read_b128 v[168:171], v166
	ds_read_b128 v[172:175], v166 offset:1024
	ds_read_b128 v[176:179], v166 offset:2048
	ds_read_b128 v[180:183], v166 offset:3072
	s_add_u32 s24, s22, 0xfffe0080
	s_addc_u32 s25, s23, -1
	s_cmp_eq_u32 s51, 4
	s_cselect_b32 s27, s15, s25
	s_cselect_b32 s26, s47, s24
	s_cselect_b32 s25, s13, s50
	s_cselect_b32 s24, s48, s49
	v_lshl_add_u64 v[160:161], s[22:23], 0, v[152:153]
	s_add_i32 m0, s21, 0xc000
	ds_read_b128 v[184:187], v167
	ds_read_b128 v[188:191], v167 offset:1024
	ds_read_b128 v[198:201], v167 offset:2048
	ds_read_b128 v[202:205], v167 offset:3072
	ds_read_b128 v[216:219], v167 offset:4096
	ds_read_b128 v[220:223], v167 offset:5120
	ds_read_b128 v[224:227], v167 offset:6144
	ds_read_b128 v[228:231], v167 offset:7168
	global_load_lds_dwordx4 v[160:161], off
	v_lshl_add_u64 v[160:161], s[22:23], 0, v[154:155]
	s_add_i32 m0, s21, 0xe000
	s_nop 0
	global_load_lds_dwordx4 v[160:161], off
	s_waitcnt vmcnt(8)
	s_waitcnt lgkmcnt(0)
	s_barrier
	v_mfma_f32_16x16x32_bf16 v[124:127], v[128:131], v[184:187], v[124:127]
	v_mfma_f32_16x16x32_bf16 v[120:123], v[136:139], v[184:187], v[120:123]
	v_mfma_f32_16x16x32_bf16 v[116:119], v[128:131], v[198:201], v[116:119]
	v_mfma_f32_16x16x32_bf16 v[112:115], v[136:139], v[198:201], v[112:115]
	v_mfma_f32_16x16x32_bf16 v[108:111], v[128:131], v[216:219], v[108:111]
	v_mfma_f32_16x16x32_bf16 v[100:103], v[136:139], v[216:219], v[100:103]
	v_mfma_f32_16x16x32_bf16 v[80:83], v[128:131], v[224:227], v[80:83]
	v_mfma_f32_16x16x32_bf16 v[72:75], v[136:139], v[224:227], v[72:75]
	v_mfma_f32_16x16x32_bf16 v[124:127], v[132:135], v[188:191], v[124:127]
	v_mfma_f32_16x16x32_bf16 v[120:123], v[140:143], v[188:191], v[120:123]
	v_mfma_f32_16x16x32_bf16 v[116:119], v[132:135], v[202:205], v[116:119]
	v_mfma_f32_16x16x32_bf16 v[112:115], v[140:143], v[202:205], v[112:115]
	v_mfma_f32_16x16x32_bf16 v[108:111], v[132:135], v[220:223], v[108:111]
	v_mfma_f32_16x16x32_bf16 v[100:103], v[140:143], v[220:223], v[100:103]
	v_mfma_f32_16x16x32_bf16 v[80:83], v[132:135], v[228:231], v[80:83]
	v_mfma_f32_16x16x32_bf16 v[72:75], v[140:143], v[228:231], v[72:75]
	v_mfma_f32_16x16x32_bf16 v[104:107], v[168:171], v[184:187], v[104:107]
	v_mfma_f32_16x16x32_bf16 v[96:99], v[176:179], v[184:187], v[96:99]
	v_mfma_f32_16x16x32_bf16 v[92:95], v[168:171], v[198:201], v[92:95]
	v_mfma_f32_16x16x32_bf16 v[88:91], v[176:179], v[198:201], v[88:91]
	v_mfma_f32_16x16x32_bf16 v[84:87], v[168:171], v[216:219], v[84:87]
	v_mfma_f32_16x16x32_bf16 v[76:79], v[176:179], v[216:219], v[76:79]
	v_mfma_f32_16x16x32_bf16 v[68:71], v[168:171], v[224:227], v[68:71]
	v_mfma_f32_16x16x32_bf16 v[64:67], v[176:179], v[224:227], v[64:67]
	v_mfma_f32_16x16x32_bf16 v[104:107], v[172:175], v[188:191], v[104:107]
	v_mfma_f32_16x16x32_bf16 v[96:99], v[180:183], v[188:191], v[96:99]
	v_mfma_f32_16x16x32_bf16 v[92:95], v[172:175], v[202:205], v[92:95]
	v_mfma_f32_16x16x32_bf16 v[88:91], v[180:183], v[202:205], v[88:91]
	v_mfma_f32_16x16x32_bf16 v[84:87], v[172:175], v[220:223], v[84:87]
	v_mfma_f32_16x16x32_bf16 v[76:79], v[180:183], v[220:223], v[76:79]
	v_mfma_f32_16x16x32_bf16 v[68:71], v[172:175], v[228:231], v[68:71]
	v_mfma_f32_16x16x32_bf16 v[64:67], v[180:183], v[228:231], v[64:67]
	s_barrier
	s_add_i32 s52, s40, s29
	v_lshl_add_u64 v[160:161], s[24:25], 0, v[146:147]
	s_mov_b32 m0, s52
	ds_read_b128 v[184:187], v167 offset:16384
	ds_read_b128 v[188:191], v167 offset:17408
	ds_read_b128 v[198:201], v167 offset:18432
	ds_read_b128 v[202:205], v167 offset:19456
	ds_read_b128 v[216:219], v167 offset:20480
	ds_read_b128 v[220:223], v167 offset:21504
	ds_read_b128 v[224:227], v167 offset:22528
	ds_read_b128 v[228:231], v167 offset:23552
	global_load_lds_dwordx4 v[160:161], off
	s_add_i32 m0, s52, 0x2000
	s_add_u32 s52, s24, 0x20000
	v_lshl_add_u64 v[192:193], s[24:25], 0, v[150:151]
	s_addc_u32 s53, s25, 0
	s_add_i32 s54, s41, s29
	global_load_lds_dwordx4 v[192:193], off
	v_lshl_add_u64 v[206:207], s[52:53], 0, v[146:147]
	s_mov_b32 m0, s54
	v_lshl_add_u64 v[210:211], s[26:27], 0, v[148:149]
	global_load_lds_dwordx4 v[206:207], off
	v_lshl_add_u64 v[206:207], s[52:53], 0, v[150:151]
	s_add_i32 m0, s54, 0x2000
	s_nop 0
	global_load_lds_dwordx4 v[206:207], off
	v_lshl_add_u64 v[206:207], s[26:27], 0, v[144:145]
	s_mov_b32 m0, s21
	s_nop 0
	global_load_lds_dwordx4 v[206:207], off
	s_mov_b32 m0, s30
	s_nop 0
	global_load_lds_dwordx4 v[210:211], off
	s_waitcnt vmcnt(8)
	s_waitcnt lgkmcnt(0)
	s_barrier
; #define PG8_STAGE(bufoff, gbase, voff) do { _Pragma("unroll") for (int _i = 0; _i < 2; ++_i) \
;         __builtin_amdgcn_global_load_lds((const unsigned*)((const char*)(gbase) + (voff)[_i]), (LAS unsigned*)(lds + (bufoff) + ldsw + _i * 8192), 16, 0, 0); } while (0)
; #define PG8_LDA(dst, b, h) do { _Pragma("unroll") for (int m = 0; m < 4; ++m) _Pragma("unroll") for (int k = 0; k < 2; ++k) dst[m][k] = *(const LAS bf16x8*)(lds + PG8_SA(b, h) + aoff + m * 2048 + k * 1024); } while (0)
; #define PG8_LDB(dst, b, h) do { _Pragma("unroll") for (int n = 0; n < 2; ++n) _Pragma("unroll") for (int k = 0; k < 2; ++k) dst[n][k] = *(const LAS bf16x8*)(lds + PG8_SB(b, h) + boff + n * 2048 + k * 1024); } while (0)
; #define PG8_MMA(ai, bj, At, Bt) do { __builtin_amdgcn_s_setprio(1); _Pragma("unroll") for (int m = 0; m < 4; ++m) _Pragma("unroll") for (int n = 0; n < 2; ++n) _Pragma("unroll") for (int k = 0; k < 2; ++k) \
;         acc[ai][bj][m][n] = __builtin_amdgcn_mfma_f32_16x16x32_bf16(Bt[n][k], At[m][k], acc[ai][bj][m][n], 0, 0, 0); __builtin_amdgcn_s_setprio(0); } while (0)
; #define PG8_WAIT_V(n) asm volatile("s_waitcnt vmcnt(" #n ")" ::: "memory")
; #define PG8_WAIT_L(n) asm volatile("s_waitcnt lgkmcnt(" #n ")" ::: "memory")
; #define PG8_BAR __builtin_amdgcn_s_barrier()
; #define PG8_SCHED __builtin_amdgcn_sched_barrier(0)
; template <class Epi, bool ALIGN_EPI, bool SP2 = PG8_SP2_DEFAULT>
; __device__ __forceinline__ void gemm_phase(LAS unsigned char* lds, const Gemm g, const StaticOrder& S, const Epi& E) {
;     ...
;             PG8_WAIT_V(8); PG8_WAIT_L(0); PG8_BAR; PG8_MMA(1, 0, At, B0); PG8_MMA(1, 1, At, B1); PG8_BAR; PG8_SCHED;
;             PG8_LDB(B0, 1, 0); PG8_LDB(B1, 1, 1); PG8_SCHED; PG8_LDA(At, 1, 0); PG8_STAGE(PG8_SA(0, 1), a2 + hstepA, voffA);
;             PG8_WAIT_V(8); PG8_WAIT_L(0); PG8_BAR; PG8_MMA(0, 0, At, B0); PG8_MMA(0, 1, At, B1); PG8_BAR; PG8_SCHED;
	v_mfma_f32_16x16x32_bf16 v[60:63], v[128:131], v[184:187], v[60:63]
	v_mfma_f32_16x16x32_bf16 v[56:59], v[136:139], v[184:187], v[56:59]
	v_mfma_f32_16x16x32_bf16 v[52:55], v[128:131], v[198:201], v[52:55]
	v_mfma_f32_16x16x32_bf16 v[44:47], v[136:139], v[198:201], v[44:47]
	v_mfma_f32_16x16x32_bf16 v[36:39], v[128:131], v[216:219], v[36:39]
	v_mfma_f32_16x16x32_bf16 v[28:31], v[136:139], v[216:219], v[28:31]
	v_mfma_f32_16x16x32_bf16 v[20:23], v[128:131], v[224:227], v[20:23]
	v_mfma_f32_16x16x32_bf16 v[12:15], v[136:139], v[224:227], v[12:15]
	v_mfma_f32_16x16x32_bf16 v[60:63], v[132:135], v[188:191], v[60:63]
	v_mfma_f32_16x16x32_bf16 v[56:59], v[140:143], v[188:191], v[56:59]
	v_mfma_f32_16x16x32_bf16 v[52:55], v[132:135], v[202:205], v[52:55]
	v_mfma_f32_16x16x32_bf16 v[44:47], v[140:143], v[202:205], v[44:47]
	v_mfma_f32_16x16x32_bf16 v[36:39], v[132:135], v[220:223], v[36:39]
	v_mfma_f32_16x16x32_bf16 v[28:31], v[140:143], v[220:223], v[28:31]
	v_mfma_f32_16x16x32_bf16 v[20:23], v[132:135], v[228:231], v[20:23]
	v_mfma_f32_16x16x32_bf16 v[12:15], v[140:143], v[228:231], v[12:15]
	v_mfma_f32_16x16x32_bf16 v[48:51], v[168:171], v[184:187], v[48:51]
	v_mfma_f32_16x16x32_bf16 v[40:43], v[176:179], v[184:187], v[40:43]
	v_mfma_f32_16x16x32_bf16 v[32:35], v[168:171], v[198:201], v[32:35]
	v_mfma_f32_16x16x32_bf16 v[24:27], v[176:179], v[198:201], v[24:27]
	v_mfma_f32_16x16x32_bf16 v[16:19], v[168:171], v[216:219], v[16:19]
	v_mfma_f32_16x16x32_bf16 v[8:11], v[176:179], v[216:219], v[8:11]
	v_mfma_f32_16x16x32_bf16 v[4:7], v[168:171], v[224:227], v[4:7]
	v_mfma_f32_16x16x32_bf16 v[0:3], v[176:179], v[224:227], v[0:3]
	v_mfma_f32_16x16x32_bf16 v[48:51], v[172:175], v[188:191], v[48:51]
	v_mfma_f32_16x16x32_bf16 v[40:43], v[180:183], v[188:191], v[40:43]
	v_mfma_f32_16x16x32_bf16 v[32:35], v[172:175], v[202:205], v[32:35]
	v_mfma_f32_16x16x32_bf16 v[24:27], v[180:183], v[202:205], v[24:27]
	v_mfma_f32_16x16x32_bf16 v[16:19], v[172:175], v[220:223], v[16:19]
	v_mfma_f32_16x16x32_bf16 v[8:11], v[180:183], v[220:223], v[8:11]
	v_mfma_f32_16x16x32_bf16 v[4:7], v[172:175], v[228:231], v[4:7]
	v_mfma_f32_16x16x32_bf16 v[0:3], v[180:183], v[228:231], v[0:3]
	s_barrier
	s_add_i32 s52, 0, 0x18000
	s_add_i32 s53, 0, 0x1c000
	v_add_u32_e32 v140, s52, v163
	v_add_u32_e32 v180, s53, v163
	ds_read_b128 v[128:131], v140
	ds_read_b128 v[132:135], v140 offset:1024
	ds_read_b128 v[136:139], v140 offset:2048
	ds_read_b128 v[140:143], v140 offset:3072
	ds_read_b128 v[168:171], v180
	ds_read_b128 v[172:175], v180 offset:1024
	ds_read_b128 v[176:179], v180 offset:2048
	ds_read_b128 v[180:183], v180 offset:3072
	s_add_u32 s26, s26, 0x20000
	s_addc_u32 s27, s27, 0
	s_mov_b32 m0, s31
	v_lshl_add_u64 v[232:233], s[26:27], 0, v[144:145]
	ds_read_b128 v[184:187], v167 offset:32768
	ds_read_b128 v[188:191], v167 offset:33792
	ds_read_b128 v[198:201], v167 offset:34816
	ds_read_b128 v[202:205], v167 offset:35840
	ds_read_b128 v[216:219], v167 offset:36864
	ds_read_b128 v[220:223], v167 offset:37888
	ds_read_b128 v[224:227], v167 offset:38912
	ds_read_b128 v[228:231], v167 offset:39936
	global_load_lds_dwordx4 v[232:233], off
	v_lshl_add_u64 v[232:233], s[26:27], 0, v[148:149]
	s_mov_b32 m0, s34
	s_nop 0
	global_load_lds_dwordx4 v[232:233], off
	s_waitcnt vmcnt(8)
	s_waitcnt lgkmcnt(0)
	s_barrier
	v_mfma_f32_16x16x32_bf16 v[124:127], v[128:131], v[184:187], v[124:127]
	v_mfma_f32_16x16x32_bf16 v[120:123], v[136:139], v[184:187], v[120:123]
	v_mfma_f32_16x16x32_bf16 v[116:119], v[128:131], v[198:201], v[116:119]
	v_mfma_f32_16x16x32_bf16 v[112:115], v[136:139], v[198:201], v[112:115]
	v_mfma_f32_16x16x32_bf16 v[108:111], v[128:131], v[216:219], v[108:111]
	v_mfma_f32_16x16x32_bf16 v[100:103], v[136:139], v[216:219], v[100:103]
	v_mfma_f32_16x16x32_bf16 v[80:83], v[128:131], v[224:227], v[80:83]
	v_mfma_f32_16x16x32_bf16 v[72:75], v[136:139], v[224:227], v[72:75]
	v_mfma_f32_16x16x32_bf16 v[124:127], v[132:135], v[188:191], v[124:127]
	v_mfma_f32_16x16x32_bf16 v[120:123], v[140:143], v[188:191], v[120:123]
	v_mfma_f32_16x16x32_bf16 v[116:119], v[132:135], v[202:205], v[116:119]
	v_mfma_f32_16x16x32_bf16 v[112:115], v[140:143], v[202:205], v[112:115]
	v_mfma_f32_16x16x32_bf16 v[108:111], v[132:135], v[220:223], v[108:111]
	v_mfma_f32_16x16x32_bf16 v[100:103], v[140:143], v[220:223], v[100:103]
	v_mfma_f32_16x16x32_bf16 v[80:83], v[132:135], v[228:231], v[80:83]
	v_mfma_f32_16x16x32_bf16 v[72:75], v[140:143], v[228:231], v[72:75]
	v_mfma_f32_16x16x32_bf16 v[104:107], v[168:171], v[184:187], v[104:107]
	v_mfma_f32_16x16x32_bf16 v[96:99], v[176:179], v[184:187], v[96:99]
	v_mfma_f32_16x16x32_bf16 v[92:95], v[168:171], v[198:201], v[92:95]
	v_mfma_f32_16x16x32_bf16 v[88:91], v[176:179], v[198:201], v[88:91]
	v_mfma_f32_16x16x32_bf16 v[84:87], v[168:171], v[216:219], v[84:87]
	v_mfma_f32_16x16x32_bf16 v[76:79], v[176:179], v[216:219], v[76:79]
	v_mfma_f32_16x16x32_bf16 v[68:71], v[168:171], v[224:227], v[68:71]
	v_mfma_f32_16x16x32_bf16 v[64:67], v[176:179], v[224:227], v[64:67]
	v_mfma_f32_16x16x32_bf16 v[104:107], v[172:175], v[188:191], v[104:107]
	v_mfma_f32_16x16x32_bf16 v[96:99], v[180:183], v[188:191], v[96:99]
	v_mfma_f32_16x16x32_bf16 v[92:95], v[172:175], v[202:205], v[92:95]
	v_mfma_f32_16x16x32_bf16 v[88:91], v[180:183], v[202:205], v[88:91]
	v_mfma_f32_16x16x32_bf16 v[84:87], v[172:175], v[220:223], v[84:87]
	v_mfma_f32_16x16x32_bf16 v[76:79], v[180:183], v[220:223], v[76:79]
	v_mfma_f32_16x16x32_bf16 v[68:71], v[172:175], v[228:231], v[68:71]
	v_mfma_f32_16x16x32_bf16 v[64:67], v[180:183], v[228:231], v[64:67]
	s_barrier
; #define PG8_STAGE(bufoff, gbase, voff) do { _Pragma("unroll") for (int _i = 0; _i < 2; ++_i) \
;         __builtin_amdgcn_global_load_lds((const unsigned*)((const char*)(gbase) + (voff)[_i]), (LAS unsigned*)(lds + (bufoff) + ldsw + _i * 8192), 16, 0, 0); } while (0)
; #define PG8_LDA(dst, b, h) do { _Pragma("unroll") for (int m = 0; m < 4; ++m) _Pragma("unroll") for (int k = 0; k < 2; ++k) dst[m][k] = *(const LAS bf16x8*)(lds + PG8_SA(b, h) + aoff + m * 2048 + k * 1024); } while (0)
; #define PG8_MMA(ai, bj, At, Bt) do { __builtin_amdgcn_s_setprio(1); _Pragma("unroll") for (int m = 0; m < 4; ++m) _Pragma("unroll") for (int n = 0; n < 2; ++n) _Pragma("unroll") for (int k = 0; k < 2; ++k) \
;         acc[ai][bj][m][n] = __builtin_amdgcn_mfma_f32_16x16x32_bf16(Bt[n][k], At[m][k], acc[ai][bj][m][n], 0, 0, 0); __builtin_amdgcn_s_setprio(0); } while (0)
; #define PG8_WAIT_V(n) asm volatile("s_waitcnt vmcnt(" #n ")" ::: "memory")
; #define PG8_WAIT_L(n) asm volatile("s_waitcnt lgkmcnt(" #n ")" ::: "memory")
; #define PG8_BAR __builtin_amdgcn_s_barrier()
; #define PG8_SCHED __builtin_amdgcn_sched_barrier(0)
; template <class Epi, bool ALIGN_EPI, bool SP2 = PG8_SP2_DEFAULT>
; __device__ __forceinline__ void gemm_phase(LAS unsigned char* lds, const Gemm g, const StaticOrder& S, const Epi& E) {
;     ...
;             PG8_LDA(At, 1, 1); PG8_STAGE(PG8_SB(1, 0), b3, voffB); PG8_STAGE(PG8_SB(1, 1), b3 + hstepB, voffB); PG8_STAGE(PG8_SA(1, 0), a3, voffA);
;             PG8_WAIT_V(8); PG8_WAIT_L(0); PG8_BAR; PG8_MMA(1, 0, At, B0); PG8_MMA(1, 1, At, B1); PG8_BAR; PG8_SCHED;
;     ...
;         if constexpr (ALIGN_EPI) { if (wr == 0) PG8_BAR; }
	s_add_i32 s26, s52, s29
	v_lshl_add_u64 v[160:161], v[160:161], 0, s[4:5]
	s_mov_b32 m0, s26
	ds_read_b128 v[184:187], v167 offset:49152
	ds_read_b128 v[188:191], v167 offset:50176
	ds_read_b128 v[198:201], v167 offset:51200
	ds_read_b128 v[202:205], v167 offset:52224
	ds_read_b128 v[216:219], v167 offset:53248
	ds_read_b128 v[220:223], v167 offset:54272
	ds_read_b128 v[224:227], v167 offset:55296
	ds_read_b128 v[228:231], v167 offset:56320
	global_load_lds_dwordx4 v[160:161], off
	s_add_i32 m0, s26, 0x2000
	s_add_u32 s24, s24, 0x20080
	v_lshl_add_u64 v[160:161], v[192:193], 0, s[4:5]
	s_addc_u32 s25, s25, 0
	s_add_i32 s26, s53, s29
	global_load_lds_dwordx4 v[160:161], off
	v_lshl_add_u64 v[160:161], s[24:25], 0, v[146:147]
	s_mov_b32 m0, s26
	s_nop 0
	global_load_lds_dwordx4 v[160:161], off
	v_lshl_add_u64 v[160:161], s[24:25], 0, v[150:151]
	s_add_i32 m0, s26, 0x2000
	s_nop 0
	global_load_lds_dwordx4 v[160:161], off
	v_lshl_add_u64 v[160:161], v[206:207], 0, s[4:5]
	s_mov_b32 m0, s36
	s_nop 0
	global_load_lds_dwordx4 v[160:161], off
	v_lshl_add_u64 v[160:161], v[210:211], 0, s[4:5]
	s_mov_b32 m0, s37
	s_nop 0
	global_load_lds_dwordx4 v[160:161], off
	s_nop 0
	s_waitcnt vmcnt(8)
	s_waitcnt lgkmcnt(0)
	s_barrier
	v_mfma_f32_16x16x32_bf16 v[60:63], v[128:131], v[184:187], v[60:63]
	v_mfma_f32_16x16x32_bf16 v[56:59], v[136:139], v[184:187], v[56:59]
	v_mfma_f32_16x16x32_bf16 v[52:55], v[128:131], v[198:201], v[52:55]
	v_mfma_f32_16x16x32_bf16 v[44:47], v[136:139], v[198:201], v[44:47]
	v_mfma_f32_16x16x32_bf16 v[36:39], v[128:131], v[216:219], v[36:39]
	v_mfma_f32_16x16x32_bf16 v[28:31], v[136:139], v[216:219], v[28:31]
	v_mfma_f32_16x16x32_bf16 v[20:23], v[128:131], v[224:227], v[20:23]
	v_mfma_f32_16x16x32_bf16 v[12:15], v[136:139], v[224:227], v[12:15]
	v_mfma_f32_16x16x32_bf16 v[60:63], v[132:135], v[188:191], v[60:63]
	v_mfma_f32_16x16x32_bf16 v[56:59], v[140:143], v[188:191], v[56:59]
	v_mfma_f32_16x16x32_bf16 v[52:55], v[132:135], v[202:205], v[52:55]
	v_mfma_f32_16x16x32_bf16 v[44:47], v[140:143], v[202:205], v[44:47]
	v_mfma_f32_16x16x32_bf16 v[36:39], v[132:135], v[220:223], v[36:39]
	v_mfma_f32_16x16x32_bf16 v[28:31], v[140:143], v[220:223], v[28:31]
	v_mfma_f32_16x16x32_bf16 v[20:23], v[132:135], v[228:231], v[20:23]
	v_mfma_f32_16x16x32_bf16 v[12:15], v[140:143], v[228:231], v[12:15]
	v_mfma_f32_16x16x32_bf16 v[48:51], v[168:171], v[184:187], v[48:51]
	v_mfma_f32_16x16x32_bf16 v[40:43], v[176:179], v[184:187], v[40:43]
	v_mfma_f32_16x16x32_bf16 v[32:35], v[168:171], v[198:201], v[32:35]
	v_mfma_f32_16x16x32_bf16 v[24:27], v[176:179], v[198:201], v[24:27]
	v_mfma_f32_16x16x32_bf16 v[16:19], v[168:171], v[216:219], v[16:19]
	v_mfma_f32_16x16x32_bf16 v[8:11], v[176:179], v[216:219], v[8:11]
	v_mfma_f32_16x16x32_bf16 v[4:7], v[168:171], v[224:227], v[4:7]
	v_mfma_f32_16x16x32_bf16 v[0:3], v[176:179], v[224:227], v[0:3]
	v_mfma_f32_16x16x32_bf16 v[48:51], v[172:175], v[188:191], v[48:51]
	v_mfma_f32_16x16x32_bf16 v[40:43], v[180:183], v[188:191], v[40:43]
	v_mfma_f32_16x16x32_bf16 v[32:35], v[172:175], v[202:205], v[32:35]
	v_mfma_f32_16x16x32_bf16 v[24:27], v[180:183], v[202:205], v[24:27]
	v_mfma_f32_16x16x32_bf16 v[16:19], v[172:175], v[220:223], v[16:19]
	v_mfma_f32_16x16x32_bf16 v[8:11], v[180:183], v[220:223], v[8:11]
	v_mfma_f32_16x16x32_bf16 v[4:7], v[172:175], v[228:231], v[4:7]
	v_mfma_f32_16x16x32_bf16 v[0:3], v[180:183], v[228:231], v[0:3]
	s_barrier
	s_add_i32 s51, s51, 2
	s_add_u32 s22, s22, 0x100
	s_addc_u32 s23, s23, 0
	s_add_u32 s49, s49, 0x100
	s_addc_u32 s50, s50, 0
	s_cmp_gt_u32 s51, 5
	s_cbranch_scc0 .LBB0_428
	s_and_b64 vcc, exec, s[6:7]
	s_cbranch_vccz .LBB0_431
	s_barrier

; #define PG8_STAGE(bufoff, gbase, voff) do { _Pragma("unroll") for (int _i = 0; _i < 2; ++_i) \
;         __builtin_amdgcn_global_load_lds((const unsigned*)((const char*)(gbase) + (voff)[_i]), (LAS unsigned*)(lds + (bufoff) + ldsw + _i * 8192), 16, 0, 0); } while (0)
; #define PG8_LDA(dst, b, h) do { _Pragma("unroll") for (int m = 0; m < 4; ++m) _Pragma("unroll") for (int k = 0; k < 2; ++k) dst[m][k] = *(const LAS bf16x8*)(lds + PG8_SA(b, h) + aoff + m * 2048 + k * 1024); } while (0)
; #define PG8_LDB(dst, b, h) do { _Pragma("unroll") for (int n = 0; n < 2; ++n) _Pragma("unroll") for (int k = 0; k < 2; ++k) dst[n][k] = *(const LAS bf16x8*)(lds + PG8_SB(b, h) + boff + n * 2048 + k * 1024); } while (0)
; #define PG8_MMA(ai, bj, At, Bt) do { __builtin_amdgcn_s_setprio(1); _Pragma("unroll") for (int m = 0; m < 4; ++m) _Pragma("unroll") for (int n = 0; n < 2; ++n) _Pragma("unroll") for (int k = 0; k < 2; ++k) \
;         acc[ai][bj][m][n] = __builtin_amdgcn_mfma_f32_16x16x32_bf16(Bt[n][k], At[m][k], acc[ai][bj][m][n], 0, 0, 0); __builtin_amdgcn_s_setprio(0); } while (0)
; #define PG8_WAIT_V(n) asm volatile("s_waitcnt vmcnt(" #n ")" ::: "memory")
; #define PG8_WAIT_L(n) asm volatile("s_waitcnt lgkmcnt(" #n ")" ::: "memory")
; #define PG8_BAR __builtin_amdgcn_s_barrier()
; #define PG8_SCHED __builtin_amdgcn_sched_barrier(0)
; template <class Epi, bool ALIGN_EPI, bool SP2 = PG8_SP2_DEFAULT>
; __device__ __forceinline__ void gemm_phase(LAS unsigned char* lds, const Gemm g, const StaticOrder& S, const Epi& E) {
;     ...
;             PG8_LDB(B0, 0, 0); PG8_LDB(B1, 0, 1); PG8_SCHED; PG8_LDA(At, 0, 0); PG8_STAGE(PG8_SA(1, 1), a1 + hstepA, voffA);
;             PG8_WAIT_V(8); PG8_WAIT_L(0); PG8_BAR; PG8_MMA(0, 0, At, B0); PG8_MMA(0, 1, At, B1); PG8_BAR; PG8_SCHED;
;             PG8_LDA(At, 0, 1); PG8_STAGE(PG8_SB(0, 0), b2, voffB); PG8_STAGE(PG8_SB(0, 1), b2 + hstepB, voffB); PG8_STAGE(PG8_SA(0, 0), a2, voffA);
.LBB0_506:
	ds_read_b128 v[144:147], v151
	ds_read_b128 v[156:159], v151 offset:1024
	ds_read_b128 v[160:163], v151 offset:2048
	ds_read_b128 v[164:167], v151 offset:3072
	ds_read_b128 v[168:171], v152
	ds_read_b128 v[172:175], v152 offset:1024
	ds_read_b128 v[176:179], v152 offset:2048
	ds_read_b128 v[180:183], v152 offset:3072
	s_add_u32 s28, s26, 0xfff00080
	s_addc_u32 s29, s27, -1
	s_cmp_eq_u32 s50, 60
	s_cselect_b32 s31, s19, s29
	s_cselect_b32 s30, s25, s28
	s_cselect_b32 s29, s3, s49
	s_cselect_b32 s28, s47, s48
	v_lshl_add_u64 v[192:193], s[26:27], 0, v[136:137]
	s_add_i32 m0, s34, 0xc000
	ds_read_b128 v[184:187], v153
	ds_read_b128 v[188:191], v153 offset:1024
	ds_read_b128 v[198:201], v153 offset:2048
	ds_read_b128 v[202:205], v153 offset:3072
	ds_read_b128 v[216:219], v153 offset:4096
	ds_read_b128 v[220:223], v153 offset:5120
	ds_read_b128 v[224:227], v153 offset:6144
	ds_read_b128 v[228:231], v153 offset:7168
	global_load_lds_dwordx4 v[192:193], off
	v_lshl_add_u64 v[192:193], s[26:27], 0, v[138:139]
	s_add_i32 m0, s34, 0xe000
	s_nop 0
	global_load_lds_dwordx4 v[192:193], off
	s_nop 0
	s_waitcnt vmcnt(8)
	s_waitcnt lgkmcnt(0)
	s_barrier
	v_mfma_f32_16x16x32_bf16 v[124:127], v[144:147], v[184:187], v[124:127]
	v_mfma_f32_16x16x32_bf16 v[120:123], v[160:163], v[184:187], v[120:123]
	v_mfma_f32_16x16x32_bf16 v[108:111], v[144:147], v[198:201], v[108:111]
	v_mfma_f32_16x16x32_bf16 v[104:107], v[160:163], v[198:201], v[104:107]
	v_mfma_f32_16x16x32_bf16 v[92:95], v[144:147], v[216:219], v[92:95]
	v_mfma_f32_16x16x32_bf16 v[88:91], v[160:163], v[216:219], v[88:91]
	v_mfma_f32_16x16x32_bf16 v[76:79], v[144:147], v[224:227], v[76:79]
	v_mfma_f32_16x16x32_bf16 v[72:75], v[160:163], v[224:227], v[72:75]
	v_mfma_f32_16x16x32_bf16 v[124:127], v[156:159], v[188:191], v[124:127]
	v_mfma_f32_16x16x32_bf16 v[120:123], v[164:167], v[188:191], v[120:123]
	v_mfma_f32_16x16x32_bf16 v[108:111], v[156:159], v[202:205], v[108:111]
	v_mfma_f32_16x16x32_bf16 v[104:107], v[164:167], v[202:205], v[104:107]
	v_mfma_f32_16x16x32_bf16 v[92:95], v[156:159], v[220:223], v[92:95]
	v_mfma_f32_16x16x32_bf16 v[88:91], v[164:167], v[220:223], v[88:91]
	v_mfma_f32_16x16x32_bf16 v[76:79], v[156:159], v[228:231], v[76:79]
	v_mfma_f32_16x16x32_bf16 v[72:75], v[164:167], v[228:231], v[72:75]
	v_mfma_f32_16x16x32_bf16 v[116:119], v[168:171], v[184:187], v[116:119]
	v_mfma_f32_16x16x32_bf16 v[112:115], v[176:179], v[184:187], v[112:115]
	v_mfma_f32_16x16x32_bf16 v[100:103], v[168:171], v[198:201], v[100:103]
	v_mfma_f32_16x16x32_bf16 v[96:99], v[176:179], v[198:201], v[96:99]
	v_mfma_f32_16x16x32_bf16 v[84:87], v[168:171], v[216:219], v[84:87]
	v_mfma_f32_16x16x32_bf16 v[80:83], v[176:179], v[216:219], v[80:83]
	v_mfma_f32_16x16x32_bf16 v[68:71], v[168:171], v[224:227], v[68:71]
	v_mfma_f32_16x16x32_bf16 v[64:67], v[176:179], v[224:227], v[64:67]
	v_mfma_f32_16x16x32_bf16 v[116:119], v[172:175], v[188:191], v[116:119]
	v_mfma_f32_16x16x32_bf16 v[112:115], v[180:183], v[188:191], v[112:115]
	v_mfma_f32_16x16x32_bf16 v[100:103], v[172:175], v[202:205], v[100:103]
	v_mfma_f32_16x16x32_bf16 v[96:99], v[180:183], v[202:205], v[96:99]
	v_mfma_f32_16x16x32_bf16 v[84:87], v[172:175], v[220:223], v[84:87]
	v_mfma_f32_16x16x32_bf16 v[80:83], v[180:183], v[220:223], v[80:83]
	v_mfma_f32_16x16x32_bf16 v[68:71], v[172:175], v[228:231], v[68:71]
	v_mfma_f32_16x16x32_bf16 v[64:67], v[180:183], v[228:231], v[64:67]
	s_barrier
	s_add_i32 s51, s44, s33
	v_lshl_add_u64 v[192:193], s[28:29], 0, v[130:131]
	s_mov_b32 m0, s51
	ds_read_b128 v[184:187], v153 offset:16384
	ds_read_b128 v[188:191], v153 offset:17408
	ds_read_b128 v[198:201], v153 offset:18432
	ds_read_b128 v[202:205], v153 offset:19456
	ds_read_b128 v[216:219], v153 offset:20480
	ds_read_b128 v[220:223], v153 offset:21504
	ds_read_b128 v[224:227], v153 offset:22528
	ds_read_b128 v[228:231], v153 offset:23552
	global_load_lds_dwordx4 v[192:193], off
	s_add_i32 m0, s51, 0x2000
	s_add_u32 s52, s28, 0x100000
	v_lshl_add_u64 v[206:207], s[28:29], 0, v[134:135]
	s_addc_u32 s53, s29, 0
	s_add_i32 s51, s45, s33
	global_load_lds_dwordx4 v[206:207], off
	v_lshl_add_u64 v[210:211], s[52:53], 0, v[130:131]
	s_mov_b32 m0, s51
	v_lshl_add_u64 v[232:233], s[30:31], 0, v[132:133]
	global_load_lds_dwordx4 v[210:211], off
	v_lshl_add_u64 v[210:211], s[52:53], 0, v[134:135]
	s_add_i32 m0, s51, 0x2000
	s_nop 0
	global_load_lds_dwordx4 v[210:211], off
	v_lshl_add_u64 v[210:211], s[30:31], 0, v[128:129]
	s_mov_b32 m0, s34
	s_nop 0
	global_load_lds_dwordx4 v[210:211], off
	s_mov_b32 m0, s35
	s_nop 0
	global_load_lds_dwordx4 v[232:233], off
	s_waitcnt vmcnt(8)
	s_waitcnt lgkmcnt(0)
	s_barrier
; #define PG8_STAGE(bufoff, gbase, voff) do { _Pragma("unroll") for (int _i = 0; _i < 2; ++_i) \
;         __builtin_amdgcn_global_load_lds((const unsigned*)((const char*)(gbase) + (voff)[_i]), (LAS unsigned*)(lds + (bufoff) + ldsw + _i * 8192), 16, 0, 0); } while (0)
; #define PG8_LDA(dst, b, h) do { _Pragma("unroll") for (int m = 0; m < 4; ++m) _Pragma("unroll") for (int k = 0; k < 2; ++k) dst[m][k] = *(const LAS bf16x8*)(lds + PG8_SA(b, h) + aoff + m * 2048 + k * 1024); } while (0)
; #define PG8_LDB(dst, b, h) do { _Pragma("unroll") for (int n = 0; n < 2; ++n) _Pragma("unroll") for (int k = 0; k < 2; ++k) dst[n][k] = *(const LAS bf16x8*)(lds + PG8_SB(b, h) + boff + n * 2048 + k * 1024); } while (0)
; #define PG8_MMA(ai, bj, At, Bt) do { __builtin_amdgcn_s_setprio(1); _Pragma("unroll") for (int m = 0; m < 4; ++m) _Pragma("unroll") for (int n = 0; n < 2; ++n) _Pragma("unroll") for (int k = 0; k < 2; ++k) \
;         acc[ai][bj][m][n] = __builtin_amdgcn_mfma_f32_16x16x32_bf16(Bt[n][k], At[m][k], acc[ai][bj][m][n], 0, 0, 0); __builtin_amdgcn_s_setprio(0); } while (0)
; #define PG8_WAIT_V(n) asm volatile("s_waitcnt vmcnt(" #n ")" ::: "memory")
; #define PG8_WAIT_L(n) asm volatile("s_waitcnt lgkmcnt(" #n ")" ::: "memory")
; #define PG8_BAR __builtin_amdgcn_s_barrier()
; #define PG8_SCHED __builtin_amdgcn_sched_barrier(0)
; template <class Epi, bool ALIGN_EPI, bool SP2 = PG8_SP2_DEFAULT>
; __device__ __forceinline__ void gemm_phase(LAS unsigned char* lds, const Gemm g, const StaticOrder& S, const Epi& E) {
;     ...
;             PG8_WAIT_V(8); PG8_WAIT_L(0); PG8_BAR; PG8_MMA(1, 0, At, B0); PG8_MMA(1, 1, At, B1); PG8_BAR; PG8_SCHED;
;             PG8_LDB(B0, 1, 0); PG8_LDB(B1, 1, 1); PG8_SCHED; PG8_LDA(At, 1, 0); PG8_STAGE(PG8_SA(0, 1), a2 + hstepA, voffA);
;             PG8_WAIT_V(8); PG8_WAIT_L(0); PG8_BAR; PG8_MMA(0, 0, At, B0); PG8_MMA(0, 1, At, B1); PG8_BAR; PG8_SCHED;
	v_mfma_f32_16x16x32_bf16 v[60:63], v[144:147], v[184:187], v[60:63]
	v_mfma_f32_16x16x32_bf16 v[56:59], v[160:163], v[184:187], v[56:59]
	v_mfma_f32_16x16x32_bf16 v[44:47], v[144:147], v[198:201], v[44:47]
	v_mfma_f32_16x16x32_bf16 v[40:43], v[160:163], v[198:201], v[40:43]
	v_mfma_f32_16x16x32_bf16 v[28:31], v[144:147], v[216:219], v[28:31]
	v_mfma_f32_16x16x32_bf16 v[24:27], v[160:163], v[216:219], v[24:27]
	v_mfma_f32_16x16x32_bf16 v[12:15], v[144:147], v[224:227], v[12:15]
	v_mfma_f32_16x16x32_bf16 v[8:11], v[160:163], v[224:227], v[8:11]
	v_mfma_f32_16x16x32_bf16 v[60:63], v[156:159], v[188:191], v[60:63]
	v_mfma_f32_16x16x32_bf16 v[56:59], v[164:167], v[188:191], v[56:59]
	v_mfma_f32_16x16x32_bf16 v[44:47], v[156:159], v[202:205], v[44:47]
	v_mfma_f32_16x16x32_bf16 v[40:43], v[164:167], v[202:205], v[40:43]
	v_mfma_f32_16x16x32_bf16 v[28:31], v[156:159], v[220:223], v[28:31]
	v_mfma_f32_16x16x32_bf16 v[24:27], v[164:167], v[220:223], v[24:27]
	v_mfma_f32_16x16x32_bf16 v[12:15], v[156:159], v[228:231], v[12:15]
	v_mfma_f32_16x16x32_bf16 v[8:11], v[164:167], v[228:231], v[8:11]
	v_mfma_f32_16x16x32_bf16 v[52:55], v[168:171], v[184:187], v[52:55]
	v_mfma_f32_16x16x32_bf16 v[48:51], v[176:179], v[184:187], v[48:51]
	v_mfma_f32_16x16x32_bf16 v[36:39], v[168:171], v[198:201], v[36:39]
	v_mfma_f32_16x16x32_bf16 v[32:35], v[176:179], v[198:201], v[32:35]
	v_mfma_f32_16x16x32_bf16 v[20:23], v[168:171], v[216:219], v[20:23]
	v_mfma_f32_16x16x32_bf16 v[16:19], v[176:179], v[216:219], v[16:19]
	v_mfma_f32_16x16x32_bf16 v[4:7], v[168:171], v[224:227], v[4:7]
	v_mfma_f32_16x16x32_bf16 v[0:3], v[176:179], v[224:227], v[0:3]
	v_mfma_f32_16x16x32_bf16 v[52:55], v[172:175], v[188:191], v[52:55]
	v_mfma_f32_16x16x32_bf16 v[48:51], v[180:183], v[188:191], v[48:51]
	v_mfma_f32_16x16x32_bf16 v[36:39], v[172:175], v[202:205], v[36:39]
	v_mfma_f32_16x16x32_bf16 v[32:35], v[180:183], v[202:205], v[32:35]
	v_mfma_f32_16x16x32_bf16 v[20:23], v[172:175], v[220:223], v[20:23]
	v_mfma_f32_16x16x32_bf16 v[16:19], v[180:183], v[220:223], v[16:19]
	v_mfma_f32_16x16x32_bf16 v[4:7], v[172:175], v[228:231], v[4:7]
	v_mfma_f32_16x16x32_bf16 v[0:3], v[180:183], v[228:231], v[0:3]
	s_barrier
	s_add_i32 s51, 0, 0x18000
	v_add_u32_e32 v155, s51, v149
	s_add_i32 s52, 0, 0x1c000
	ds_read_b128 v[144:147], v155
	ds_read_b128 v[156:159], v155 offset:1024
	ds_read_b128 v[160:163], v155 offset:2048
	ds_read_b128 v[164:167], v155 offset:3072
	v_add_u32_e32 v155, s52, v149
	ds_read_b128 v[168:171], v155
	ds_read_b128 v[172:175], v155 offset:1024
	ds_read_b128 v[176:179], v155 offset:2048
	ds_read_b128 v[180:183], v155 offset:3072
	s_add_u32 s30, s30, 0x100000
	s_addc_u32 s31, s31, 0
	s_mov_b32 m0, s36
	v_lshl_add_u64 v[234:235], s[30:31], 0, v[128:129]
	ds_read_b128 v[184:187], v153 offset:32768
	ds_read_b128 v[188:191], v153 offset:33792
	ds_read_b128 v[198:201], v153 offset:34816
	ds_read_b128 v[202:205], v153 offset:35840
	ds_read_b128 v[216:219], v153 offset:36864
	ds_read_b128 v[220:223], v153 offset:37888
	ds_read_b128 v[224:227], v153 offset:38912
	ds_read_b128 v[228:231], v153 offset:39936
	global_load_lds_dwordx4 v[234:235], off
	v_lshl_add_u64 v[234:235], s[30:31], 0, v[132:133]
	s_mov_b32 m0, s37
	s_nop 0
	global_load_lds_dwordx4 v[234:235], off
	s_waitcnt vmcnt(8)
	s_waitcnt lgkmcnt(0)
	s_barrier
	v_mfma_f32_16x16x32_bf16 v[124:127], v[144:147], v[184:187], v[124:127]
	v_mfma_f32_16x16x32_bf16 v[120:123], v[160:163], v[184:187], v[120:123]
	v_mfma_f32_16x16x32_bf16 v[108:111], v[144:147], v[198:201], v[108:111]
	v_mfma_f32_16x16x32_bf16 v[104:107], v[160:163], v[198:201], v[104:107]
	v_mfma_f32_16x16x32_bf16 v[92:95], v[144:147], v[216:219], v[92:95]
	v_mfma_f32_16x16x32_bf16 v[88:91], v[160:163], v[216:219], v[88:91]
	v_mfma_f32_16x16x32_bf16 v[76:79], v[144:147], v[224:227], v[76:79]
	v_mfma_f32_16x16x32_bf16 v[72:75], v[160:163], v[224:227], v[72:75]
	v_mfma_f32_16x16x32_bf16 v[124:127], v[156:159], v[188:191], v[124:127]
	v_mfma_f32_16x16x32_bf16 v[120:123], v[164:167], v[188:191], v[120:123]
	v_mfma_f32_16x16x32_bf16 v[108:111], v[156:159], v[202:205], v[108:111]
	v_mfma_f32_16x16x32_bf16 v[104:107], v[164:167], v[202:205], v[104:107]
	v_mfma_f32_16x16x32_bf16 v[92:95], v[156:159], v[220:223], v[92:95]
	v_mfma_f32_16x16x32_bf16 v[88:91], v[164:167], v[220:223], v[88:91]
	v_mfma_f32_16x16x32_bf16 v[76:79], v[156:159], v[228:231], v[76:79]
	v_mfma_f32_16x16x32_bf16 v[72:75], v[164:167], v[228:231], v[72:75]
	v_mfma_f32_16x16x32_bf16 v[116:119], v[168:171], v[184:187], v[116:119]
	v_mfma_f32_16x16x32_bf16 v[112:115], v[176:179], v[184:187], v[112:115]
	v_mfma_f32_16x16x32_bf16 v[100:103], v[168:171], v[198:201], v[100:103]
	v_mfma_f32_16x16x32_bf16 v[96:99], v[176:179], v[198:201], v[96:99]
	v_mfma_f32_16x16x32_bf16 v[84:87], v[168:171], v[216:219], v[84:87]
	v_mfma_f32_16x16x32_bf16 v[80:83], v[176:179], v[216:219], v[80:83]
	v_mfma_f32_16x16x32_bf16 v[68:71], v[168:171], v[224:227], v[68:71]
	v_mfma_f32_16x16x32_bf16 v[64:67], v[176:179], v[224:227], v[64:67]
	v_mfma_f32_16x16x32_bf16 v[116:119], v[172:175], v[188:191], v[116:119]
	v_mfma_f32_16x16x32_bf16 v[112:115], v[180:183], v[188:191], v[112:115]
	v_mfma_f32_16x16x32_bf16 v[100:103], v[172:175], v[202:205], v[100:103]
	v_mfma_f32_16x16x32_bf16 v[96:99], v[180:183], v[202:205], v[96:99]
	v_mfma_f32_16x16x32_bf16 v[84:87], v[172:175], v[220:223], v[84:87]
	v_mfma_f32_16x16x32_bf16 v[80:83], v[180:183], v[220:223], v[80:83]
	v_mfma_f32_16x16x32_bf16 v[68:71], v[172:175], v[228:231], v[68:71]
	v_mfma_f32_16x16x32_bf16 v[64:67], v[180:183], v[228:231], v[64:67]
	s_barrier
; #define PG8_STAGE(bufoff, gbase, voff) do { _Pragma("unroll") for (int _i = 0; _i < 2; ++_i) \
;         __builtin_amdgcn_global_load_lds((const unsigned*)((const char*)(gbase) + (voff)[_i]), (LAS unsigned*)(lds + (bufoff) + ldsw + _i * 8192), 16, 0, 0); } while (0)
; #define PG8_LDA(dst, b, h) do { _Pragma("unroll") for (int m = 0; m < 4; ++m) _Pragma("unroll") for (int k = 0; k < 2; ++k) dst[m][k] = *(const LAS bf16x8*)(lds + PG8_SA(b, h) + aoff + m * 2048 + k * 1024); } while (0)
; #define PG8_MMA(ai, bj, At, Bt) do { __builtin_amdgcn_s_setprio(1); _Pragma("unroll") for (int m = 0; m < 4; ++m) _Pragma("unroll") for (int n = 0; n < 2; ++n) _Pragma("unroll") for (int k = 0; k < 2; ++k) \
;         acc[ai][bj][m][n] = __builtin_amdgcn_mfma_f32_16x16x32_bf16(Bt[n][k], At[m][k], acc[ai][bj][m][n], 0, 0, 0); __builtin_amdgcn_s_setprio(0); } while (0)
; #define PG8_WAIT_V(n) asm volatile("s_waitcnt vmcnt(" #n ")" ::: "memory")
; #define PG8_WAIT_L(n) asm volatile("s_waitcnt lgkmcnt(" #n ")" ::: "memory")
; #define PG8_BAR __builtin_amdgcn_s_barrier()
; #define PG8_SCHED __builtin_amdgcn_sched_barrier(0)
; template <class Epi, bool ALIGN_EPI, bool SP2 = PG8_SP2_DEFAULT>
; __device__ __forceinline__ void gemm_phase(LAS unsigned char* lds, const Gemm g, const StaticOrder& S, const Epi& E) {
;     ...
;             PG8_LDA(At, 1, 1); PG8_STAGE(PG8_SB(1, 0), b3, voffB); PG8_STAGE(PG8_SB(1, 1), b3 + hstepB, voffB); PG8_STAGE(PG8_SA(1, 0), a3, voffA);
;             PG8_WAIT_V(8); PG8_WAIT_L(0); PG8_BAR; PG8_MMA(1, 0, At, B0); PG8_MMA(1, 1, At, B1); PG8_BAR; PG8_SCHED;
;     ...
;         if constexpr (ALIGN_EPI) { if (wr == 0) PG8_BAR; }
	s_add_i32 s30, s51, s33
	v_lshl_add_u64 v[192:193], v[192:193], 0, s[14:15]
	s_mov_b32 m0, s30
	ds_read_b128 v[184:187], v153 offset:49152
	ds_read_b128 v[188:191], v153 offset:50176
	ds_read_b128 v[198:201], v153 offset:51200
	ds_read_b128 v[202:205], v153 offset:52224
	ds_read_b128 v[216:219], v153 offset:53248
	ds_read_b128 v[220:223], v153 offset:54272
	ds_read_b128 v[224:227], v153 offset:55296
	ds_read_b128 v[228:231], v153 offset:56320
	global_load_lds_dwordx4 v[192:193], off
	s_add_i32 m0, s30, 0x2000
	s_add_u32 s28, s28, 0x100080
	v_lshl_add_u64 v[192:193], v[206:207], 0, s[14:15]
	s_addc_u32 s29, s29, 0
	s_add_i32 s30, s52, s33
	global_load_lds_dwordx4 v[192:193], off
	v_lshl_add_u64 v[192:193], s[28:29], 0, v[130:131]
	s_mov_b32 m0, s30
	s_nop 0
	global_load_lds_dwordx4 v[192:193], off
	v_lshl_add_u64 v[192:193], s[28:29], 0, v[134:135]
	s_add_i32 m0, s30, 0x2000
	s_nop 0
	global_load_lds_dwordx4 v[192:193], off
	v_lshl_add_u64 v[192:193], v[210:211], 0, s[14:15]
	s_mov_b32 m0, s39
	s_nop 0
	global_load_lds_dwordx4 v[192:193], off
	v_lshl_add_u64 v[192:193], v[232:233], 0, s[14:15]
	s_mov_b32 m0, s40
	s_nop 0
	global_load_lds_dwordx4 v[192:193], off
	s_nop 0
	s_waitcnt vmcnt(8)
	s_waitcnt lgkmcnt(0)
	s_barrier
	v_mfma_f32_16x16x32_bf16 v[60:63], v[144:147], v[184:187], v[60:63]
	v_mfma_f32_16x16x32_bf16 v[56:59], v[160:163], v[184:187], v[56:59]
	v_mfma_f32_16x16x32_bf16 v[44:47], v[144:147], v[198:201], v[44:47]
	v_mfma_f32_16x16x32_bf16 v[40:43], v[160:163], v[198:201], v[40:43]
	v_mfma_f32_16x16x32_bf16 v[28:31], v[144:147], v[216:219], v[28:31]
	v_mfma_f32_16x16x32_bf16 v[24:27], v[160:163], v[216:219], v[24:27]
	v_mfma_f32_16x16x32_bf16 v[12:15], v[144:147], v[224:227], v[12:15]
	v_mfma_f32_16x16x32_bf16 v[8:11], v[160:163], v[224:227], v[8:11]
	v_mfma_f32_16x16x32_bf16 v[60:63], v[156:159], v[188:191], v[60:63]
	v_mfma_f32_16x16x32_bf16 v[56:59], v[164:167], v[188:191], v[56:59]
	v_mfma_f32_16x16x32_bf16 v[44:47], v[156:159], v[202:205], v[44:47]
	v_mfma_f32_16x16x32_bf16 v[40:43], v[164:167], v[202:205], v[40:43]
	v_mfma_f32_16x16x32_bf16 v[28:31], v[156:159], v[220:223], v[28:31]
	v_mfma_f32_16x16x32_bf16 v[24:27], v[164:167], v[220:223], v[24:27]
	v_mfma_f32_16x16x32_bf16 v[12:15], v[156:159], v[228:231], v[12:15]
	v_mfma_f32_16x16x32_bf16 v[8:11], v[164:167], v[228:231], v[8:11]
	v_mfma_f32_16x16x32_bf16 v[52:55], v[168:171], v[184:187], v[52:55]
	v_mfma_f32_16x16x32_bf16 v[48:51], v[176:179], v[184:187], v[48:51]
	v_mfma_f32_16x16x32_bf16 v[36:39], v[168:171], v[198:201], v[36:39]
	v_mfma_f32_16x16x32_bf16 v[32:35], v[176:179], v[198:201], v[32:35]
	v_mfma_f32_16x16x32_bf16 v[20:23], v[168:171], v[216:219], v[20:23]
	v_mfma_f32_16x16x32_bf16 v[16:19], v[176:179], v[216:219], v[16:19]
	v_mfma_f32_16x16x32_bf16 v[4:7], v[168:171], v[224:227], v[4:7]
	v_mfma_f32_16x16x32_bf16 v[0:3], v[176:179], v[224:227], v[0:3]
	v_mfma_f32_16x16x32_bf16 v[52:55], v[172:175], v[188:191], v[52:55]
	v_mfma_f32_16x16x32_bf16 v[48:51], v[180:183], v[188:191], v[48:51]
	v_mfma_f32_16x16x32_bf16 v[36:39], v[172:175], v[202:205], v[36:39]
	v_mfma_f32_16x16x32_bf16 v[32:35], v[180:183], v[202:205], v[32:35]
	v_mfma_f32_16x16x32_bf16 v[20:23], v[172:175], v[220:223], v[20:23]
	v_mfma_f32_16x16x32_bf16 v[16:19], v[180:183], v[220:223], v[16:19]
	v_mfma_f32_16x16x32_bf16 v[4:7], v[172:175], v[228:231], v[4:7]
	v_mfma_f32_16x16x32_bf16 v[0:3], v[180:183], v[228:231], v[0:3]
	s_barrier
	s_add_i32 s50, s50, 2
	s_add_u32 s26, s26, 0x100
	s_addc_u32 s27, s27, 0
	s_add_u32 s48, s48, 0x100
	s_addc_u32 s49, s49, 0
	s_cmp_gt_u32 s50, 61
	s_cbranch_scc0 .LBB0_506
	s_and_b64 vcc, exec, s[16:17]
	s_cbranch_vccz .LBB0_509
	s_barrier

; #define PG8_STAGE(bufoff, gbase, voff) do { _Pragma("unroll") for (int _i = 0; _i < 2; ++_i) \
;         __builtin_amdgcn_global_load_lds((const unsigned*)((const char*)(gbase) + (voff)[_i]), (LAS unsigned*)(lds + (bufoff) + ldsw + _i * 8192), 16, 0, 0); } while (0)
; #define PG8_LDA(dst, b, h) do { _Pragma("unroll") for (int m = 0; m < 4; ++m) _Pragma("unroll") for (int k = 0; k < 2; ++k) dst[m][k] = *(const LAS bf16x8*)(lds + PG8_SA(b, h) + aoff + m * 2048 + k * 1024); } while (0)
; #define PG8_LDB(dst, b, h) do { _Pragma("unroll") for (int n = 0; n < 2; ++n) _Pragma("unroll") for (int k = 0; k < 2; ++k) dst[n][k] = *(const LAS bf16x8*)(lds + PG8_SB(b, h) + boff + n * 2048 + k * 1024); } while (0)
; #define PG8_MMA(ai, bj, At, Bt) do { __builtin_amdgcn_s_setprio(1); _Pragma("unroll") for (int m = 0; m < 4; ++m) _Pragma("unroll") for (int n = 0; n < 2; ++n) _Pragma("unroll") for (int k = 0; k < 2; ++k) \
;         acc[ai][bj][m][n] = __builtin_amdgcn_mfma_f32_16x16x32_bf16(Bt[n][k], At[m][k], acc[ai][bj][m][n], 0, 0, 0); __builtin_amdgcn_s_setprio(0); } while (0)
; #define PG8_WAIT_V(n) asm volatile("s_waitcnt vmcnt(" #n ")" ::: "memory")
; #define PG8_WAIT_L(n) asm volatile("s_waitcnt lgkmcnt(" #n ")" ::: "memory")
; #define PG8_BAR __builtin_amdgcn_s_barrier()
; #define PG8_SCHED __builtin_amdgcn_sched_barrier(0)
; template <class Epi, bool ALIGN_EPI, bool SP2 = PG8_SP2_DEFAULT>
; __device__ __forceinline__ void gemm_phase(LAS unsigned char* lds, const Gemm g, const StaticOrder& S, const Epi& E) {
;     ...
;             PG8_LDB(B0, 0, 0); PG8_LDB(B1, 0, 1); PG8_SCHED; PG8_LDA(At, 0, 0); PG8_STAGE(PG8_SA(1, 1), a1 + hstepA, voffA);
;             PG8_WAIT_V(8); PG8_WAIT_L(0); PG8_BAR; PG8_MMA(0, 0, At, B0); PG8_MMA(0, 1, At, B1); PG8_BAR; PG8_SCHED;
;             PG8_LDA(At, 0, 1); PG8_STAGE(PG8_SB(0, 0), b2, voffB); PG8_STAGE(PG8_SB(0, 1), b2 + hstepB, voffB); PG8_STAGE(PG8_SA(0, 0), a2, voffA);
.LBB0_598:
	ds_read_b128 v[146:149], v155
	ds_read_b128 v[160:163], v155 offset:1024
	ds_read_b128 v[164:167], v155 offset:2048
	ds_read_b128 v[168:171], v155 offset:3072
	ds_read_b128 v[172:175], v156
	ds_read_b128 v[176:179], v156 offset:1024
	ds_read_b128 v[180:183], v156 offset:2048
	ds_read_b128 v[184:187], v156 offset:3072
	s_add_u32 s24, s22, 0xfff00080
	s_addc_u32 s25, s23, -1
	s_cmp_eq_u32 s47, 60
	s_cselect_b32 s27, s3, s25
	s_cselect_b32 s26, s7, s24
	s_cselect_b32 s25, s9, s45
	s_cselect_b32 s24, s17, s44
	v_lshl_add_u64 v[192:193], s[22:23], 0, v[138:139]
	s_add_i32 m0, s30, 0xc000
	ds_read_b128 v[188:191], v157
	ds_read_b128 v[198:201], v157 offset:1024
	ds_read_b128 v[202:205], v157 offset:2048
	ds_read_b128 v[214:217], v157 offset:3072
	ds_read_b128 v[218:221], v157 offset:4096
	ds_read_b128 v[222:225], v157 offset:5120
	ds_read_b128 v[226:229], v157 offset:6144
	ds_read_b128 v[230:233], v157 offset:7168
	global_load_lds_dwordx4 v[192:193], off
	v_lshl_add_u64 v[192:193], s[22:23], 0, v[140:141]
	s_add_i32 m0, s30, 0xe000
	s_nop 0
	global_load_lds_dwordx4 v[192:193], off
	s_waitcnt vmcnt(8)
	s_waitcnt lgkmcnt(0)
	s_barrier
	v_mfma_f32_16x16x32_bf16 v[124:127], v[146:149], v[188:191], v[124:127]
	v_mfma_f32_16x16x32_bf16 v[120:123], v[164:167], v[188:191], v[120:123]
	v_mfma_f32_16x16x32_bf16 v[108:111], v[146:149], v[202:205], v[108:111]
	v_mfma_f32_16x16x32_bf16 v[104:107], v[164:167], v[202:205], v[104:107]
	v_mfma_f32_16x16x32_bf16 v[92:95], v[146:149], v[218:221], v[92:95]
	v_mfma_f32_16x16x32_bf16 v[88:91], v[164:167], v[218:221], v[88:91]
	v_mfma_f32_16x16x32_bf16 v[76:79], v[146:149], v[226:229], v[76:79]
	v_mfma_f32_16x16x32_bf16 v[72:75], v[164:167], v[226:229], v[72:75]
	v_mfma_f32_16x16x32_bf16 v[124:127], v[160:163], v[198:201], v[124:127]
	v_mfma_f32_16x16x32_bf16 v[120:123], v[168:171], v[198:201], v[120:123]
	v_mfma_f32_16x16x32_bf16 v[108:111], v[160:163], v[214:217], v[108:111]
	v_mfma_f32_16x16x32_bf16 v[104:107], v[168:171], v[214:217], v[104:107]
	v_mfma_f32_16x16x32_bf16 v[92:95], v[160:163], v[222:225], v[92:95]
	v_mfma_f32_16x16x32_bf16 v[88:91], v[168:171], v[222:225], v[88:91]
	v_mfma_f32_16x16x32_bf16 v[76:79], v[160:163], v[230:233], v[76:79]
	v_mfma_f32_16x16x32_bf16 v[72:75], v[168:171], v[230:233], v[72:75]
	v_mfma_f32_16x16x32_bf16 v[116:119], v[172:175], v[188:191], v[116:119]
	v_mfma_f32_16x16x32_bf16 v[112:115], v[180:183], v[188:191], v[112:115]
	v_mfma_f32_16x16x32_bf16 v[100:103], v[172:175], v[202:205], v[100:103]
	v_mfma_f32_16x16x32_bf16 v[96:99], v[180:183], v[202:205], v[96:99]
	v_mfma_f32_16x16x32_bf16 v[84:87], v[172:175], v[218:221], v[84:87]
	v_mfma_f32_16x16x32_bf16 v[80:83], v[180:183], v[218:221], v[80:83]
	v_mfma_f32_16x16x32_bf16 v[68:71], v[172:175], v[226:229], v[68:71]
	v_mfma_f32_16x16x32_bf16 v[64:67], v[180:183], v[226:229], v[64:67]
	v_mfma_f32_16x16x32_bf16 v[116:119], v[176:179], v[198:201], v[116:119]
	v_mfma_f32_16x16x32_bf16 v[112:115], v[184:187], v[198:201], v[112:115]
	v_mfma_f32_16x16x32_bf16 v[100:103], v[176:179], v[214:217], v[100:103]
	v_mfma_f32_16x16x32_bf16 v[96:99], v[184:187], v[214:217], v[96:99]
	v_mfma_f32_16x16x32_bf16 v[84:87], v[176:179], v[222:225], v[84:87]
	v_mfma_f32_16x16x32_bf16 v[80:83], v[184:187], v[222:225], v[80:83]
	v_mfma_f32_16x16x32_bf16 v[68:71], v[176:179], v[230:233], v[68:71]
	v_mfma_f32_16x16x32_bf16 v[64:67], v[184:187], v[230:233], v[64:67]
	s_barrier
	s_add_i32 s48, s41, s29
	v_lshl_add_u64 v[192:193], s[24:25], 0, v[130:131]
	s_mov_b32 m0, s48
	ds_read_b128 v[188:191], v157 offset:16384
	ds_read_b128 v[198:201], v157 offset:17408
	ds_read_b128 v[202:205], v157 offset:18432
	ds_read_b128 v[214:217], v157 offset:19456
	ds_read_b128 v[218:221], v157 offset:20480
	ds_read_b128 v[222:225], v157 offset:21504
	ds_read_b128 v[226:229], v157 offset:22528
	ds_read_b128 v[230:233], v157 offset:23552
	global_load_lds_dwordx4 v[192:193], off
	s_add_i32 m0, s48, 0x2000
	s_add_u32 s48, s24, 0x100000
	v_lshl_add_u64 v[206:207], s[24:25], 0, v[134:135]
	s_addc_u32 s49, s25, 0
	s_add_i32 s50, s42, s29
	global_load_lds_dwordx4 v[206:207], off
	v_lshl_add_u64 v[210:211], s[48:49], 0, v[130:131]
	s_mov_b32 m0, s50
	v_lshl_add_u64 v[234:235], s[26:27], 0, v[132:133]
	global_load_lds_dwordx4 v[210:211], off
	v_lshl_add_u64 v[210:211], s[48:49], 0, v[134:135]
	s_add_i32 m0, s50, 0x2000
	s_nop 0
	global_load_lds_dwordx4 v[210:211], off
	v_lshl_add_u64 v[210:211], s[26:27], 0, v[128:129]
	s_mov_b32 m0, s30
	s_nop 0
	global_load_lds_dwordx4 v[210:211], off
	s_mov_b32 m0, s31
	s_nop 0
	global_load_lds_dwordx4 v[234:235], off
	s_waitcnt vmcnt(8)
	s_waitcnt lgkmcnt(0)
	s_barrier
; #define PG8_STAGE(bufoff, gbase, voff) do { _Pragma("unroll") for (int _i = 0; _i < 2; ++_i) \
;         __builtin_amdgcn_global_load_lds((const unsigned*)((const char*)(gbase) + (voff)[_i]), (LAS unsigned*)(lds + (bufoff) + ldsw + _i * 8192), 16, 0, 0); } while (0)
; #define PG8_LDA(dst, b, h) do { _Pragma("unroll") for (int m = 0; m < 4; ++m) _Pragma("unroll") for (int k = 0; k < 2; ++k) dst[m][k] = *(const LAS bf16x8*)(lds + PG8_SA(b, h) + aoff + m * 2048 + k * 1024); } while (0)
; #define PG8_LDB(dst, b, h) do { _Pragma("unroll") for (int n = 0; n < 2; ++n) _Pragma("unroll") for (int k = 0; k < 2; ++k) dst[n][k] = *(const LAS bf16x8*)(lds + PG8_SB(b, h) + boff + n * 2048 + k * 1024); } while (0)
; #define PG8_MMA(ai, bj, At, Bt) do { __builtin_amdgcn_s_setprio(1); _Pragma("unroll") for (int m = 0; m < 4; ++m) _Pragma("unroll") for (int n = 0; n < 2; ++n) _Pragma("unroll") for (int k = 0; k < 2; ++k) \
;         acc[ai][bj][m][n] = __builtin_amdgcn_mfma_f32_16x16x32_bf16(Bt[n][k], At[m][k], acc[ai][bj][m][n], 0, 0, 0); __builtin_amdgcn_s_setprio(0); } while (0)
; #define PG8_WAIT_V(n) asm volatile("s_waitcnt vmcnt(" #n ")" ::: "memory")
; #define PG8_WAIT_L(n) asm volatile("s_waitcnt lgkmcnt(" #n ")" ::: "memory")
; #define PG8_BAR __builtin_amdgcn_s_barrier()
; #define PG8_SCHED __builtin_amdgcn_sched_barrier(0)
; template <class Epi, bool ALIGN_EPI, bool SP2 = PG8_SP2_DEFAULT>
; __device__ __forceinline__ void gemm_phase(LAS unsigned char* lds, const Gemm g, const StaticOrder& S, const Epi& E) {
;     ...
;             PG8_WAIT_V(8); PG8_WAIT_L(0); PG8_BAR; PG8_MMA(1, 0, At, B0); PG8_MMA(1, 1, At, B1); PG8_BAR; PG8_SCHED;
;             PG8_LDB(B0, 1, 0); PG8_LDB(B1, 1, 1); PG8_SCHED; PG8_LDA(At, 1, 0); PG8_STAGE(PG8_SA(0, 1), a2 + hstepA, voffA);
;             PG8_WAIT_V(8); PG8_WAIT_L(0); PG8_BAR; PG8_MMA(0, 0, At, B0); PG8_MMA(0, 1, At, B1); PG8_BAR; PG8_SCHED;
	v_mfma_f32_16x16x32_bf16 v[60:63], v[146:149], v[188:191], v[60:63]
	v_mfma_f32_16x16x32_bf16 v[56:59], v[164:167], v[188:191], v[56:59]
	v_mfma_f32_16x16x32_bf16 v[44:47], v[146:149], v[202:205], v[44:47]
	v_mfma_f32_16x16x32_bf16 v[40:43], v[164:167], v[202:205], v[40:43]
	v_mfma_f32_16x16x32_bf16 v[28:31], v[146:149], v[218:221], v[28:31]
	v_mfma_f32_16x16x32_bf16 v[24:27], v[164:167], v[218:221], v[24:27]
	v_mfma_f32_16x16x32_bf16 v[12:15], v[146:149], v[226:229], v[12:15]
	v_mfma_f32_16x16x32_bf16 v[8:11], v[164:167], v[226:229], v[8:11]
	v_mfma_f32_16x16x32_bf16 v[60:63], v[160:163], v[198:201], v[60:63]
	v_mfma_f32_16x16x32_bf16 v[56:59], v[168:171], v[198:201], v[56:59]
	v_mfma_f32_16x16x32_bf16 v[44:47], v[160:163], v[214:217], v[44:47]
	v_mfma_f32_16x16x32_bf16 v[40:43], v[168:171], v[214:217], v[40:43]
	v_mfma_f32_16x16x32_bf16 v[28:31], v[160:163], v[222:225], v[28:31]
	v_mfma_f32_16x16x32_bf16 v[24:27], v[168:171], v[222:225], v[24:27]
	v_mfma_f32_16x16x32_bf16 v[12:15], v[160:163], v[230:233], v[12:15]
	v_mfma_f32_16x16x32_bf16 v[8:11], v[168:171], v[230:233], v[8:11]
	v_mfma_f32_16x16x32_bf16 v[52:55], v[172:175], v[188:191], v[52:55]
	v_mfma_f32_16x16x32_bf16 v[48:51], v[180:183], v[188:191], v[48:51]
	v_mfma_f32_16x16x32_bf16 v[36:39], v[172:175], v[202:205], v[36:39]
	v_mfma_f32_16x16x32_bf16 v[32:35], v[180:183], v[202:205], v[32:35]
	v_mfma_f32_16x16x32_bf16 v[20:23], v[172:175], v[218:221], v[20:23]
	v_mfma_f32_16x16x32_bf16 v[16:19], v[180:183], v[218:221], v[16:19]
	v_mfma_f32_16x16x32_bf16 v[4:7], v[172:175], v[226:229], v[4:7]
	v_mfma_f32_16x16x32_bf16 v[0:3], v[180:183], v[226:229], v[0:3]
	v_mfma_f32_16x16x32_bf16 v[52:55], v[176:179], v[198:201], v[52:55]
	v_mfma_f32_16x16x32_bf16 v[48:51], v[184:187], v[198:201], v[48:51]
	v_mfma_f32_16x16x32_bf16 v[36:39], v[176:179], v[214:217], v[36:39]
	v_mfma_f32_16x16x32_bf16 v[32:35], v[184:187], v[214:217], v[32:35]
	v_mfma_f32_16x16x32_bf16 v[20:23], v[176:179], v[222:225], v[20:23]
	v_mfma_f32_16x16x32_bf16 v[16:19], v[184:187], v[222:225], v[16:19]
	v_mfma_f32_16x16x32_bf16 v[4:7], v[176:179], v[230:233], v[4:7]
	v_mfma_f32_16x16x32_bf16 v[0:3], v[184:187], v[230:233], v[0:3]
	s_barrier
	s_add_i32 s48, 0, 0x18000
	v_add_u32_e32 v150, s48, v152
	s_add_i32 s49, 0, 0x1c000
	ds_read_b128 v[146:149], v150
	ds_read_b128 v[160:163], v150 offset:1024
	ds_read_b128 v[164:167], v150 offset:2048
	ds_read_b128 v[168:171], v150 offset:3072
	v_add_u32_e32 v150, s49, v152
	ds_read_b128 v[172:175], v150
	ds_read_b128 v[176:179], v150 offset:1024
	ds_read_b128 v[180:183], v150 offset:2048
	ds_read_b128 v[184:187], v150 offset:3072
	s_add_u32 s26, s26, 0x100000
	s_addc_u32 s27, s27, 0
	s_mov_b32 m0, s33
	v_lshl_add_u64 v[236:237], s[26:27], 0, v[128:129]
	ds_read_b128 v[188:191], v157 offset:32768
	ds_read_b128 v[198:201], v157 offset:33792
	ds_read_b128 v[202:205], v157 offset:34816
	ds_read_b128 v[214:217], v157 offset:35840
	ds_read_b128 v[218:221], v157 offset:36864
	ds_read_b128 v[222:225], v157 offset:37888
	ds_read_b128 v[226:229], v157 offset:38912
	ds_read_b128 v[230:233], v157 offset:39936
	global_load_lds_dwordx4 v[236:237], off
	v_lshl_add_u64 v[236:237], s[26:27], 0, v[132:133]
	s_mov_b32 m0, s34
	s_nop 0
	global_load_lds_dwordx4 v[236:237], off
	s_waitcnt vmcnt(8)
	s_waitcnt lgkmcnt(0)
	s_barrier
	v_mfma_f32_16x16x32_bf16 v[124:127], v[146:149], v[188:191], v[124:127]
	v_mfma_f32_16x16x32_bf16 v[120:123], v[164:167], v[188:191], v[120:123]
	v_mfma_f32_16x16x32_bf16 v[108:111], v[146:149], v[202:205], v[108:111]
	v_mfma_f32_16x16x32_bf16 v[104:107], v[164:167], v[202:205], v[104:107]
	v_mfma_f32_16x16x32_bf16 v[92:95], v[146:149], v[218:221], v[92:95]
	v_mfma_f32_16x16x32_bf16 v[88:91], v[164:167], v[218:221], v[88:91]
	v_mfma_f32_16x16x32_bf16 v[76:79], v[146:149], v[226:229], v[76:79]
	v_mfma_f32_16x16x32_bf16 v[72:75], v[164:167], v[226:229], v[72:75]
	v_mfma_f32_16x16x32_bf16 v[124:127], v[160:163], v[198:201], v[124:127]
	v_mfma_f32_16x16x32_bf16 v[120:123], v[168:171], v[198:201], v[120:123]
	v_mfma_f32_16x16x32_bf16 v[108:111], v[160:163], v[214:217], v[108:111]
	v_mfma_f32_16x16x32_bf16 v[104:107], v[168:171], v[214:217], v[104:107]
	v_mfma_f32_16x16x32_bf16 v[92:95], v[160:163], v[222:225], v[92:95]
	v_mfma_f32_16x16x32_bf16 v[88:91], v[168:171], v[222:225], v[88:91]
	v_mfma_f32_16x16x32_bf16 v[76:79], v[160:163], v[230:233], v[76:79]
	v_mfma_f32_16x16x32_bf16 v[72:75], v[168:171], v[230:233], v[72:75]
	v_mfma_f32_16x16x32_bf16 v[116:119], v[172:175], v[188:191], v[116:119]
	v_mfma_f32_16x16x32_bf16 v[112:115], v[180:183], v[188:191], v[112:115]
	v_mfma_f32_16x16x32_bf16 v[100:103], v[172:175], v[202:205], v[100:103]
	v_mfma_f32_16x16x32_bf16 v[96:99], v[180:183], v[202:205], v[96:99]
	v_mfma_f32_16x16x32_bf16 v[84:87], v[172:175], v[218:221], v[84:87]
	v_mfma_f32_16x16x32_bf16 v[80:83], v[180:183], v[218:221], v[80:83]
	v_mfma_f32_16x16x32_bf16 v[68:71], v[172:175], v[226:229], v[68:71]
	v_mfma_f32_16x16x32_bf16 v[64:67], v[180:183], v[226:229], v[64:67]
	v_mfma_f32_16x16x32_bf16 v[116:119], v[176:179], v[198:201], v[116:119]
	v_mfma_f32_16x16x32_bf16 v[112:115], v[184:187], v[198:201], v[112:115]
	v_mfma_f32_16x16x32_bf16 v[100:103], v[176:179], v[214:217], v[100:103]
	v_mfma_f32_16x16x32_bf16 v[96:99], v[184:187], v[214:217], v[96:99]
	v_mfma_f32_16x16x32_bf16 v[84:87], v[176:179], v[222:225], v[84:87]
	v_mfma_f32_16x16x32_bf16 v[80:83], v[184:187], v[222:225], v[80:83]
	v_mfma_f32_16x16x32_bf16 v[68:71], v[176:179], v[230:233], v[68:71]
	v_mfma_f32_16x16x32_bf16 v[64:67], v[184:187], v[230:233], v[64:67]
	s_barrier
; #define PG8_STAGE(bufoff, gbase, voff) do { _Pragma("unroll") for (int _i = 0; _i < 2; ++_i) \
;         __builtin_amdgcn_global_load_lds((const unsigned*)((const char*)(gbase) + (voff)[_i]), (LAS unsigned*)(lds + (bufoff) + ldsw + _i * 8192), 16, 0, 0); } while (0)
; #define PG8_LDA(dst, b, h) do { _Pragma("unroll") for (int m = 0; m < 4; ++m) _Pragma("unroll") for (int k = 0; k < 2; ++k) dst[m][k] = *(const LAS bf16x8*)(lds + PG8_SA(b, h) + aoff + m * 2048 + k * 1024); } while (0)
; #define PG8_MMA(ai, bj, At, Bt) do { __builtin_amdgcn_s_setprio(1); _Pragma("unroll") for (int m = 0; m < 4; ++m) _Pragma("unroll") for (int n = 0; n < 2; ++n) _Pragma("unroll") for (int k = 0; k < 2; ++k) \
;         acc[ai][bj][m][n] = __builtin_amdgcn_mfma_f32_16x16x32_bf16(Bt[n][k], At[m][k], acc[ai][bj][m][n], 0, 0, 0); __builtin_amdgcn_s_setprio(0); } while (0)
; #define PG8_WAIT_V(n) asm volatile("s_waitcnt vmcnt(" #n ")" ::: "memory")
; #define PG8_WAIT_L(n) asm volatile("s_waitcnt lgkmcnt(" #n ")" ::: "memory")
; #define PG8_BAR __builtin_amdgcn_s_barrier()
; #define PG8_SCHED __builtin_amdgcn_sched_barrier(0)
; template <class Epi, bool ALIGN_EPI, bool SP2 = PG8_SP2_DEFAULT>
; __device__ __forceinline__ void gemm_phase(LAS unsigned char* lds, const Gemm g, const StaticOrder& S, const Epi& E) {
;     ...
;             PG8_LDA(At, 1, 1); PG8_STAGE(PG8_SB(1, 0), b3, voffB); PG8_STAGE(PG8_SB(1, 1), b3 + hstepB, voffB); PG8_STAGE(PG8_SA(1, 0), a3, voffA);
;             PG8_WAIT_V(8); PG8_WAIT_L(0); PG8_BAR; PG8_MMA(1, 0, At, B0); PG8_MMA(1, 1, At, B1); PG8_BAR; PG8_SCHED;
;     ...
;         if constexpr (ALIGN_EPI) { if (wr == 0) PG8_BAR; }
	s_add_i32 s26, s48, s29
	v_lshl_add_u64 v[192:193], v[192:193], 0, s[12:13]
	s_mov_b32 m0, s26
	ds_read_b128 v[188:191], v157 offset:49152
	ds_read_b128 v[198:201], v157 offset:50176
	ds_read_b128 v[202:205], v157 offset:51200
	ds_read_b128 v[214:217], v157 offset:52224
	ds_read_b128 v[218:221], v157 offset:53248
	ds_read_b128 v[222:225], v157 offset:54272
	ds_read_b128 v[226:229], v157 offset:55296
	ds_read_b128 v[230:233], v157 offset:56320
	global_load_lds_dwordx4 v[192:193], off
	s_add_i32 m0, s26, 0x2000
	s_add_u32 s24, s24, 0x100080
	v_lshl_add_u64 v[192:193], v[206:207], 0, s[12:13]
	s_addc_u32 s25, s25, 0
	s_add_i32 s26, s49, s29
	global_load_lds_dwordx4 v[192:193], off
	v_lshl_add_u64 v[192:193], s[24:25], 0, v[130:131]
	s_mov_b32 m0, s26
	s_nop 0
	global_load_lds_dwordx4 v[192:193], off
	v_lshl_add_u64 v[192:193], s[24:25], 0, v[134:135]
	s_add_i32 m0, s26, 0x2000
	s_nop 0
	global_load_lds_dwordx4 v[192:193], off
	v_lshl_add_u64 v[192:193], v[210:211], 0, s[12:13]
	s_mov_b32 m0, s36
	s_nop 0
	global_load_lds_dwordx4 v[192:193], off
	v_lshl_add_u64 v[192:193], v[234:235], 0, s[12:13]
	s_mov_b32 m0, s37
	s_nop 0
	global_load_lds_dwordx4 v[192:193], off
	s_nop 0
	s_waitcnt vmcnt(8)
	s_waitcnt lgkmcnt(0)
	s_barrier
	v_mfma_f32_16x16x32_bf16 v[60:63], v[146:149], v[188:191], v[60:63]
	v_mfma_f32_16x16x32_bf16 v[56:59], v[164:167], v[188:191], v[56:59]
	v_mfma_f32_16x16x32_bf16 v[44:47], v[146:149], v[202:205], v[44:47]
	v_mfma_f32_16x16x32_bf16 v[40:43], v[164:167], v[202:205], v[40:43]
	v_mfma_f32_16x16x32_bf16 v[28:31], v[146:149], v[218:221], v[28:31]
	v_mfma_f32_16x16x32_bf16 v[24:27], v[164:167], v[218:221], v[24:27]
	v_mfma_f32_16x16x32_bf16 v[12:15], v[146:149], v[226:229], v[12:15]
	v_mfma_f32_16x16x32_bf16 v[8:11], v[164:167], v[226:229], v[8:11]
	v_mfma_f32_16x16x32_bf16 v[60:63], v[160:163], v[198:201], v[60:63]
	v_mfma_f32_16x16x32_bf16 v[56:59], v[168:171], v[198:201], v[56:59]
	v_mfma_f32_16x16x32_bf16 v[44:47], v[160:163], v[214:217], v[44:47]
	v_mfma_f32_16x16x32_bf16 v[40:43], v[168:171], v[214:217], v[40:43]
	v_mfma_f32_16x16x32_bf16 v[28:31], v[160:163], v[222:225], v[28:31]
	v_mfma_f32_16x16x32_bf16 v[24:27], v[168:171], v[222:225], v[24:27]
	v_mfma_f32_16x16x32_bf16 v[12:15], v[160:163], v[230:233], v[12:15]
	v_mfma_f32_16x16x32_bf16 v[8:11], v[168:171], v[230:233], v[8:11]
	v_mfma_f32_16x16x32_bf16 v[52:55], v[172:175], v[188:191], v[52:55]
	v_mfma_f32_16x16x32_bf16 v[48:51], v[180:183], v[188:191], v[48:51]
	v_mfma_f32_16x16x32_bf16 v[36:39], v[172:175], v[202:205], v[36:39]
	v_mfma_f32_16x16x32_bf16 v[32:35], v[180:183], v[202:205], v[32:35]
	v_mfma_f32_16x16x32_bf16 v[20:23], v[172:175], v[218:221], v[20:23]
	v_mfma_f32_16x16x32_bf16 v[16:19], v[180:183], v[218:221], v[16:19]
	v_mfma_f32_16x16x32_bf16 v[4:7], v[172:175], v[226:229], v[4:7]
	v_mfma_f32_16x16x32_bf16 v[0:3], v[180:183], v[226:229], v[0:3]
	v_mfma_f32_16x16x32_bf16 v[52:55], v[176:179], v[198:201], v[52:55]
	v_mfma_f32_16x16x32_bf16 v[48:51], v[184:187], v[198:201], v[48:51]
	v_mfma_f32_16x16x32_bf16 v[36:39], v[176:179], v[214:217], v[36:39]
	v_mfma_f32_16x16x32_bf16 v[32:35], v[184:187], v[214:217], v[32:35]
	v_mfma_f32_16x16x32_bf16 v[20:23], v[176:179], v[222:225], v[20:23]
	v_mfma_f32_16x16x32_bf16 v[16:19], v[184:187], v[222:225], v[16:19]
	v_mfma_f32_16x16x32_bf16 v[4:7], v[176:179], v[230:233], v[4:7]
	v_mfma_f32_16x16x32_bf16 v[0:3], v[184:187], v[230:233], v[0:3]
	s_barrier
	s_add_i32 s47, s47, 2
	s_add_u32 s22, s22, 0x100
	s_addc_u32 s23, s23, 0
	s_add_u32 s44, s44, 0x100
	s_addc_u32 s45, s45, 0
	s_cmp_gt_u32 s47, 61
	s_cbranch_scc0 .LBB0_598
	s_and_b64 vcc, exec, s[14:15]
	s_cbranch_vccz .LBB0_601
	s_barrier

; #define PG8_STAGE(bufoff, gbase, voff) do { _Pragma("unroll") for (int _i = 0; _i < 2; ++_i) \
;         __builtin_amdgcn_global_load_lds((const unsigned*)((const char*)(gbase) + (voff)[_i]), (LAS unsigned*)(lds + (bufoff) + ldsw + _i * 8192), 16, 0, 0); } while (0)
; #define PG8_LDA(dst, b, h) do { _Pragma("unroll") for (int m = 0; m < 4; ++m) _Pragma("unroll") for (int k = 0; k < 2; ++k) dst[m][k] = *(const LAS bf16x8*)(lds + PG8_SA(b, h) + aoff + m * 2048 + k * 1024); } while (0)
; #define PG8_LDB(dst, b, h) do { _Pragma("unroll") for (int n = 0; n < 2; ++n) _Pragma("unroll") for (int k = 0; k < 2; ++k) dst[n][k] = *(const LAS bf16x8*)(lds + PG8_SB(b, h) + boff + n * 2048 + k * 1024); } while (0)
; #define PG8_MMA(ai, bj, At, Bt) do { __builtin_amdgcn_s_setprio(1); _Pragma("unroll") for (int m = 0; m < 4; ++m) _Pragma("unroll") for (int n = 0; n < 2; ++n) _Pragma("unroll") for (int k = 0; k < 2; ++k) \
;         acc[ai][bj][m][n] = __builtin_amdgcn_mfma_f32_16x16x32_bf16(Bt[n][k], At[m][k], acc[ai][bj][m][n], 0, 0, 0); __builtin_amdgcn_s_setprio(0); } while (0)
; #define PG8_WAIT_V(n) asm volatile("s_waitcnt vmcnt(" #n ")" ::: "memory")
; #define PG8_WAIT_L(n) asm volatile("s_waitcnt lgkmcnt(" #n ")" ::: "memory")
; #define PG8_BAR __builtin_amdgcn_s_barrier()
; #define PG8_SCHED __builtin_amdgcn_sched_barrier(0)
; template <class Epi, bool ALIGN_EPI, bool SP2 = PG8_SP2_DEFAULT>
; __device__ __forceinline__ void gemm_phase(LAS unsigned char* lds, const Gemm g, const StaticOrder& S, const Epi& E) {
;     ...
;             PG8_LDB(B0, 0, 0); PG8_LDB(B1, 0, 1); PG8_SCHED; PG8_LDA(At, 0, 0); PG8_STAGE(PG8_SA(1, 1), a1 + hstepA, voffA);
;             PG8_WAIT_V(8); PG8_WAIT_L(0); PG8_BAR; PG8_MMA(0, 0, At, B0); PG8_MMA(0, 1, At, B1); PG8_BAR; PG8_SCHED;
;             PG8_LDA(At, 0, 1); PG8_STAGE(PG8_SB(0, 0), b2, voffB); PG8_STAGE(PG8_SB(0, 1), b2 + hstepB, voffB); PG8_STAGE(PG8_SA(0, 0), a2, voffA);
.LBB0_804:
	ds_read_b128 v[144:147], v153
	ds_read_b128 v[156:159], v153 offset:1024
	ds_read_b128 v[160:163], v153 offset:2048
	ds_read_b128 v[164:167], v153 offset:3072
	ds_read_b128 v[168:171], v154
	ds_read_b128 v[172:175], v154 offset:1024
	ds_read_b128 v[176:179], v154 offset:2048
	ds_read_b128 v[180:183], v154 offset:3072
	s_add_u32 s22, s20, 0x100
	s_addc_u32 s23, s21, 0
	s_cmpk_eq_i32 s49, 0xa8
	s_cselect_b32 s27, s5, s23
	s_cselect_b32 s26, s4, s22
	s_cselect_b32 s25, s19, s48
	s_cselect_b32 s24, s18, s47
	v_lshl_add_u64 v[148:149], s[20:21], 0, v[136:137]
	s_add_i32 m0, s31, 0xc000
	ds_read_b128 v[184:187], v155
	ds_read_b128 v[188:191], v155 offset:1024
	ds_read_b128 v[192:195], v155 offset:2048
	ds_read_b128 v[196:199], v155 offset:3072
	ds_read_b128 v[200:203], v155 offset:4096
	ds_read_b128 v[204:207], v155 offset:5120
	ds_read_b128 v[208:211], v155 offset:6144
	ds_read_b128 v[212:215], v155 offset:7168
	global_load_lds_dwordx4 v[148:149], off
	v_lshl_add_u64 v[148:149], s[20:21], 0, v[138:139]
	s_add_i32 m0, s31, 0xe000
	s_nop 0
	global_load_lds_dwordx4 v[148:149], off
	s_waitcnt vmcnt(8)
	s_waitcnt lgkmcnt(0)
	s_barrier
	v_mfma_f32_16x16x32_bf16 v[124:127], v[144:147], v[184:187], v[124:127]
	v_mfma_f32_16x16x32_bf16 v[120:123], v[160:163], v[184:187], v[120:123]
	v_mfma_f32_16x16x32_bf16 v[108:111], v[144:147], v[192:195], v[108:111]
	v_mfma_f32_16x16x32_bf16 v[104:107], v[160:163], v[192:195], v[104:107]
	v_mfma_f32_16x16x32_bf16 v[92:95], v[144:147], v[200:203], v[92:95]
	v_mfma_f32_16x16x32_bf16 v[88:91], v[160:163], v[200:203], v[88:91]
	v_mfma_f32_16x16x32_bf16 v[76:79], v[144:147], v[208:211], v[76:79]
	v_mfma_f32_16x16x32_bf16 v[72:75], v[160:163], v[208:211], v[72:75]
	v_mfma_f32_16x16x32_bf16 v[124:127], v[156:159], v[188:191], v[124:127]
	v_mfma_f32_16x16x32_bf16 v[120:123], v[164:167], v[188:191], v[120:123]
	v_mfma_f32_16x16x32_bf16 v[108:111], v[156:159], v[196:199], v[108:111]
	v_mfma_f32_16x16x32_bf16 v[104:107], v[164:167], v[196:199], v[104:107]
	v_mfma_f32_16x16x32_bf16 v[92:95], v[156:159], v[204:207], v[92:95]
	v_mfma_f32_16x16x32_bf16 v[88:91], v[164:167], v[204:207], v[88:91]
	v_mfma_f32_16x16x32_bf16 v[76:79], v[156:159], v[212:215], v[76:79]
	v_mfma_f32_16x16x32_bf16 v[72:75], v[164:167], v[212:215], v[72:75]
	v_mfma_f32_16x16x32_bf16 v[116:119], v[168:171], v[184:187], v[116:119]
	v_mfma_f32_16x16x32_bf16 v[112:115], v[176:179], v[184:187], v[112:115]
	v_mfma_f32_16x16x32_bf16 v[100:103], v[168:171], v[192:195], v[100:103]
	v_mfma_f32_16x16x32_bf16 v[96:99], v[176:179], v[192:195], v[96:99]
	v_mfma_f32_16x16x32_bf16 v[84:87], v[168:171], v[200:203], v[84:87]
	v_mfma_f32_16x16x32_bf16 v[80:83], v[176:179], v[200:203], v[80:83]
	v_mfma_f32_16x16x32_bf16 v[68:71], v[168:171], v[208:211], v[68:71]
	v_mfma_f32_16x16x32_bf16 v[64:67], v[176:179], v[208:211], v[64:67]
	v_mfma_f32_16x16x32_bf16 v[116:119], v[172:175], v[188:191], v[116:119]
	v_mfma_f32_16x16x32_bf16 v[112:115], v[180:183], v[188:191], v[112:115]
	v_mfma_f32_16x16x32_bf16 v[100:103], v[172:175], v[196:199], v[100:103]
	v_mfma_f32_16x16x32_bf16 v[96:99], v[180:183], v[196:199], v[96:99]
	v_mfma_f32_16x16x32_bf16 v[84:87], v[172:175], v[204:207], v[84:87]
	v_mfma_f32_16x16x32_bf16 v[80:83], v[180:183], v[204:207], v[80:83]
	v_mfma_f32_16x16x32_bf16 v[68:71], v[172:175], v[212:215], v[68:71]
	v_mfma_f32_16x16x32_bf16 v[64:67], v[180:183], v[212:215], v[64:67]
	s_barrier
	s_add_i32 s20, s40, s28
	v_lshl_add_u64 v[148:149], s[24:25], 0, v[130:131]
	s_mov_b32 m0, s20
	ds_read_b128 v[184:187], v155 offset:16384
	ds_read_b128 v[188:191], v155 offset:17408
	ds_read_b128 v[192:195], v155 offset:18432
	ds_read_b128 v[196:199], v155 offset:19456
	ds_read_b128 v[200:203], v155 offset:20480
	ds_read_b128 v[204:207], v155 offset:21504
	ds_read_b128 v[208:211], v155 offset:22528
	ds_read_b128 v[212:215], v155 offset:23552
	global_load_lds_dwordx4 v[148:149], off
	s_add_i32 m0, s20, 0x2000
	s_add_u32 s20, s24, 0x2b0000
	v_lshl_add_u64 v[216:217], s[24:25], 0, v[134:135]
	s_addc_u32 s21, s25, 0
	s_add_i32 s50, s41, s28
	global_load_lds_dwordx4 v[216:217], off
	v_lshl_add_u64 v[218:219], s[20:21], 0, v[130:131]
	s_mov_b32 m0, s50
	v_lshl_add_u64 v[220:221], s[26:27], 0, v[132:133]
	global_load_lds_dwordx4 v[218:219], off
	v_lshl_add_u64 v[218:219], s[20:21], 0, v[134:135]
	s_add_i32 m0, s50, 0x2000
	s_nop 0
	global_load_lds_dwordx4 v[218:219], off
	v_lshl_add_u64 v[218:219], s[26:27], 0, v[128:129]
	s_mov_b32 m0, s31
	s_nop 0
	global_load_lds_dwordx4 v[218:219], off
	s_mov_b32 m0, s33
	s_nop 0
	global_load_lds_dwordx4 v[220:221], off
	s_waitcnt vmcnt(8)
	s_waitcnt lgkmcnt(0)
	s_barrier
; #define PG8_STAGE(bufoff, gbase, voff) do { _Pragma("unroll") for (int _i = 0; _i < 2; ++_i) \
;         __builtin_amdgcn_global_load_lds((const unsigned*)((const char*)(gbase) + (voff)[_i]), (LAS unsigned*)(lds + (bufoff) + ldsw + _i * 8192), 16, 0, 0); } while (0)
; #define PG8_LDA(dst, b, h) do { _Pragma("unroll") for (int m = 0; m < 4; ++m) _Pragma("unroll") for (int k = 0; k < 2; ++k) dst[m][k] = *(const LAS bf16x8*)(lds + PG8_SA(b, h) + aoff + m * 2048 + k * 1024); } while (0)
; #define PG8_LDB(dst, b, h) do { _Pragma("unroll") for (int n = 0; n < 2; ++n) _Pragma("unroll") for (int k = 0; k < 2; ++k) dst[n][k] = *(const LAS bf16x8*)(lds + PG8_SB(b, h) + boff + n * 2048 + k * 1024); } while (0)
; #define PG8_MMA(ai, bj, At, Bt) do { __builtin_amdgcn_s_setprio(1); _Pragma("unroll") for (int m = 0; m < 4; ++m) _Pragma("unroll") for (int n = 0; n < 2; ++n) _Pragma("unroll") for (int k = 0; k < 2; ++k) \
;         acc[ai][bj][m][n] = __builtin_amdgcn_mfma_f32_16x16x32_bf16(Bt[n][k], At[m][k], acc[ai][bj][m][n], 0, 0, 0); __builtin_amdgcn_s_setprio(0); } while (0)
; #define PG8_WAIT_V(n) asm volatile("s_waitcnt vmcnt(" #n ")" ::: "memory")
; #define PG8_WAIT_L(n) asm volatile("s_waitcnt lgkmcnt(" #n ")" ::: "memory")
; #define PG8_BAR __builtin_amdgcn_s_barrier()
; #define PG8_SCHED __builtin_amdgcn_sched_barrier(0)
; template <class Epi, bool ALIGN_EPI, bool SP2 = PG8_SP2_DEFAULT>
; __device__ __forceinline__ void gemm_phase(LAS unsigned char* lds, const Gemm g, const StaticOrder& S, const Epi& E) {
;     ...
;             PG8_WAIT_V(8); PG8_WAIT_L(0); PG8_BAR; PG8_MMA(1, 0, At, B0); PG8_MMA(1, 1, At, B1); PG8_BAR; PG8_SCHED;
;             PG8_LDB(B0, 1, 0); PG8_LDB(B1, 1, 1); PG8_SCHED; PG8_LDA(At, 1, 0); PG8_STAGE(PG8_SA(0, 1), a2 + hstepA, voffA);
;             PG8_WAIT_V(8); PG8_WAIT_L(0); PG8_BAR; PG8_MMA(0, 0, At, B0); PG8_MMA(0, 1, At, B1); PG8_BAR; PG8_SCHED;
	v_mfma_f32_16x16x32_bf16 v[60:63], v[144:147], v[184:187], v[60:63]
	v_mfma_f32_16x16x32_bf16 v[56:59], v[160:163], v[184:187], v[56:59]
	v_mfma_f32_16x16x32_bf16 v[44:47], v[144:147], v[192:195], v[44:47]
	v_mfma_f32_16x16x32_bf16 v[40:43], v[160:163], v[192:195], v[40:43]
	v_mfma_f32_16x16x32_bf16 v[28:31], v[144:147], v[200:203], v[28:31]
	v_mfma_f32_16x16x32_bf16 v[24:27], v[160:163], v[200:203], v[24:27]
	v_mfma_f32_16x16x32_bf16 v[12:15], v[144:147], v[208:211], v[12:15]
	v_mfma_f32_16x16x32_bf16 v[8:11], v[160:163], v[208:211], v[8:11]
	v_mfma_f32_16x16x32_bf16 v[60:63], v[156:159], v[188:191], v[60:63]
	v_mfma_f32_16x16x32_bf16 v[56:59], v[164:167], v[188:191], v[56:59]
	v_mfma_f32_16x16x32_bf16 v[44:47], v[156:159], v[196:199], v[44:47]
	v_mfma_f32_16x16x32_bf16 v[40:43], v[164:167], v[196:199], v[40:43]
	v_mfma_f32_16x16x32_bf16 v[28:31], v[156:159], v[204:207], v[28:31]
	v_mfma_f32_16x16x32_bf16 v[24:27], v[164:167], v[204:207], v[24:27]
	v_mfma_f32_16x16x32_bf16 v[12:15], v[156:159], v[212:215], v[12:15]
	v_mfma_f32_16x16x32_bf16 v[8:11], v[164:167], v[212:215], v[8:11]
	v_mfma_f32_16x16x32_bf16 v[52:55], v[168:171], v[184:187], v[52:55]
	v_mfma_f32_16x16x32_bf16 v[48:51], v[176:179], v[184:187], v[48:51]
	v_mfma_f32_16x16x32_bf16 v[36:39], v[168:171], v[192:195], v[36:39]
	v_mfma_f32_16x16x32_bf16 v[32:35], v[176:179], v[192:195], v[32:35]
	v_mfma_f32_16x16x32_bf16 v[20:23], v[168:171], v[200:203], v[20:23]
	v_mfma_f32_16x16x32_bf16 v[16:19], v[176:179], v[200:203], v[16:19]
	v_mfma_f32_16x16x32_bf16 v[4:7], v[168:171], v[208:211], v[4:7]
	v_mfma_f32_16x16x32_bf16 v[0:3], v[176:179], v[208:211], v[0:3]
	v_mfma_f32_16x16x32_bf16 v[52:55], v[172:175], v[188:191], v[52:55]
	v_mfma_f32_16x16x32_bf16 v[48:51], v[180:183], v[188:191], v[48:51]
	v_mfma_f32_16x16x32_bf16 v[36:39], v[172:175], v[196:199], v[36:39]
	v_mfma_f32_16x16x32_bf16 v[32:35], v[180:183], v[196:199], v[32:35]
	v_mfma_f32_16x16x32_bf16 v[20:23], v[172:175], v[204:207], v[20:23]
	v_mfma_f32_16x16x32_bf16 v[16:19], v[180:183], v[204:207], v[16:19]
	v_mfma_f32_16x16x32_bf16 v[4:7], v[172:175], v[212:215], v[4:7]
	v_mfma_f32_16x16x32_bf16 v[0:3], v[180:183], v[212:215], v[0:3]
	s_barrier
	s_add_i32 s50, 0, 0x18000
	s_add_i32 s51, 0, 0x1c000
	v_add_u32_e32 v164, s50, v151
	v_add_u32_e32 v180, s51, v151
	ds_read_b128 v[144:147], v164
	ds_read_b128 v[156:159], v164 offset:1024
	ds_read_b128 v[160:163], v164 offset:2048
	ds_read_b128 v[164:167], v164 offset:3072
	ds_read_b128 v[168:171], v180
	ds_read_b128 v[172:175], v180 offset:1024
	ds_read_b128 v[176:179], v180 offset:2048
	ds_read_b128 v[180:183], v180 offset:3072
	s_add_u32 s20, s26, 0x2b0000
	s_addc_u32 s21, s27, 0
	s_mov_b32 m0, s34
	v_lshl_add_u64 v[222:223], s[20:21], 0, v[128:129]
	ds_read_b128 v[184:187], v155 offset:32768
	ds_read_b128 v[188:191], v155 offset:33792
	ds_read_b128 v[192:195], v155 offset:34816
	ds_read_b128 v[196:199], v155 offset:35840
	ds_read_b128 v[200:203], v155 offset:36864
	ds_read_b128 v[204:207], v155 offset:37888
	ds_read_b128 v[208:211], v155 offset:38912
	ds_read_b128 v[212:215], v155 offset:39936
	global_load_lds_dwordx4 v[222:223], off
	v_lshl_add_u64 v[222:223], s[20:21], 0, v[132:133]
	s_mov_b32 m0, s35
	s_nop 0
	global_load_lds_dwordx4 v[222:223], off
	s_waitcnt vmcnt(8)
	s_waitcnt lgkmcnt(0)
	s_barrier
	v_mfma_f32_16x16x32_bf16 v[124:127], v[144:147], v[184:187], v[124:127]
	v_mfma_f32_16x16x32_bf16 v[120:123], v[160:163], v[184:187], v[120:123]
	v_mfma_f32_16x16x32_bf16 v[108:111], v[144:147], v[192:195], v[108:111]
	v_mfma_f32_16x16x32_bf16 v[104:107], v[160:163], v[192:195], v[104:107]
	v_mfma_f32_16x16x32_bf16 v[92:95], v[144:147], v[200:203], v[92:95]
	v_mfma_f32_16x16x32_bf16 v[88:91], v[160:163], v[200:203], v[88:91]
	v_mfma_f32_16x16x32_bf16 v[76:79], v[144:147], v[208:211], v[76:79]
	v_mfma_f32_16x16x32_bf16 v[72:75], v[160:163], v[208:211], v[72:75]
	v_mfma_f32_16x16x32_bf16 v[124:127], v[156:159], v[188:191], v[124:127]
	v_mfma_f32_16x16x32_bf16 v[120:123], v[164:167], v[188:191], v[120:123]
	v_mfma_f32_16x16x32_bf16 v[108:111], v[156:159], v[196:199], v[108:111]
	v_mfma_f32_16x16x32_bf16 v[104:107], v[164:167], v[196:199], v[104:107]
	v_mfma_f32_16x16x32_bf16 v[92:95], v[156:159], v[204:207], v[92:95]
	v_mfma_f32_16x16x32_bf16 v[88:91], v[164:167], v[204:207], v[88:91]
	v_mfma_f32_16x16x32_bf16 v[76:79], v[156:159], v[212:215], v[76:79]
	v_mfma_f32_16x16x32_bf16 v[72:75], v[164:167], v[212:215], v[72:75]
	v_mfma_f32_16x16x32_bf16 v[116:119], v[168:171], v[184:187], v[116:119]
	v_mfma_f32_16x16x32_bf16 v[112:115], v[176:179], v[184:187], v[112:115]
	v_mfma_f32_16x16x32_bf16 v[100:103], v[168:171], v[192:195], v[100:103]
	v_mfma_f32_16x16x32_bf16 v[96:99], v[176:179], v[192:195], v[96:99]
	v_mfma_f32_16x16x32_bf16 v[84:87], v[168:171], v[200:203], v[84:87]
	v_mfma_f32_16x16x32_bf16 v[80:83], v[176:179], v[200:203], v[80:83]
	v_mfma_f32_16x16x32_bf16 v[68:71], v[168:171], v[208:211], v[68:71]
	v_mfma_f32_16x16x32_bf16 v[64:67], v[176:179], v[208:211], v[64:67]
	v_mfma_f32_16x16x32_bf16 v[116:119], v[172:175], v[188:191], v[116:119]
	v_mfma_f32_16x16x32_bf16 v[112:115], v[180:183], v[188:191], v[112:115]
	v_mfma_f32_16x16x32_bf16 v[100:103], v[172:175], v[196:199], v[100:103]
	v_mfma_f32_16x16x32_bf16 v[96:99], v[180:183], v[196:199], v[96:99]
	v_mfma_f32_16x16x32_bf16 v[84:87], v[172:175], v[204:207], v[84:87]
	v_mfma_f32_16x16x32_bf16 v[80:83], v[180:183], v[204:207], v[80:83]
	v_mfma_f32_16x16x32_bf16 v[68:71], v[172:175], v[212:215], v[68:71]
	v_mfma_f32_16x16x32_bf16 v[64:67], v[180:183], v[212:215], v[64:67]
	s_barrier
; #define PG8_STAGE(bufoff, gbase, voff) do { _Pragma("unroll") for (int _i = 0; _i < 2; ++_i) \
;         __builtin_amdgcn_global_load_lds((const unsigned*)((const char*)(gbase) + (voff)[_i]), (LAS unsigned*)(lds + (bufoff) + ldsw + _i * 8192), 16, 0, 0); } while (0)
; #define PG8_LDA(dst, b, h) do { _Pragma("unroll") for (int m = 0; m < 4; ++m) _Pragma("unroll") for (int k = 0; k < 2; ++k) dst[m][k] = *(const LAS bf16x8*)(lds + PG8_SA(b, h) + aoff + m * 2048 + k * 1024); } while (0)
; #define PG8_MMA(ai, bj, At, Bt) do { __builtin_amdgcn_s_setprio(1); _Pragma("unroll") for (int m = 0; m < 4; ++m) _Pragma("unroll") for (int n = 0; n < 2; ++n) _Pragma("unroll") for (int k = 0; k < 2; ++k) \
;         acc[ai][bj][m][n] = __builtin_amdgcn_mfma_f32_16x16x32_bf16(Bt[n][k], At[m][k], acc[ai][bj][m][n], 0, 0, 0); __builtin_amdgcn_s_setprio(0); } while (0)
; #define PG8_WAIT_V(n) asm volatile("s_waitcnt vmcnt(" #n ")" ::: "memory")
; #define PG8_WAIT_L(n) asm volatile("s_waitcnt lgkmcnt(" #n ")" ::: "memory")
; #define PG8_BAR __builtin_amdgcn_s_barrier()
; #define PG8_SCHED __builtin_amdgcn_sched_barrier(0)
; template <class Epi, bool ALIGN_EPI, bool SP2 = PG8_SP2_DEFAULT>
; __device__ __forceinline__ void gemm_phase(LAS unsigned char* lds, const Gemm g, const StaticOrder& S, const Epi& E) {
;     ...
;             PG8_LDA(At, 1, 1); PG8_STAGE(PG8_SB(1, 0), b3, voffB); PG8_STAGE(PG8_SB(1, 1), b3 + hstepB, voffB); PG8_STAGE(PG8_SA(1, 0), a3, voffA);
;             PG8_WAIT_V(8); PG8_WAIT_L(0); PG8_BAR; PG8_MMA(1, 0, At, B0); PG8_MMA(1, 1, At, B1); PG8_BAR; PG8_SCHED;
;     ...
;         if constexpr (ALIGN_EPI) { if (wr == 0) PG8_BAR; }
	s_add_i32 s20, s50, s28
	v_lshl_add_u64 v[148:149], v[148:149], 0, s[6:7]
	s_mov_b32 m0, s20
	ds_read_b128 v[184:187], v155 offset:49152
	ds_read_b128 v[188:191], v155 offset:50176
	ds_read_b128 v[192:195], v155 offset:51200
	ds_read_b128 v[196:199], v155 offset:52224
	ds_read_b128 v[200:203], v155 offset:53248
	ds_read_b128 v[204:207], v155 offset:54272
	ds_read_b128 v[208:211], v155 offset:55296
	ds_read_b128 v[212:215], v155 offset:56320
	global_load_lds_dwordx4 v[148:149], off
	s_add_i32 m0, s20, 0x2000
	s_add_u32 s20, s24, 0x2b0080
	v_lshl_add_u64 v[148:149], v[216:217], 0, s[6:7]
	s_addc_u32 s21, s25, 0
	s_add_i32 s24, s51, s28
	global_load_lds_dwordx4 v[148:149], off
	v_lshl_add_u64 v[148:149], s[20:21], 0, v[130:131]
	s_mov_b32 m0, s24
	s_nop 0
	global_load_lds_dwordx4 v[148:149], off
	v_lshl_add_u64 v[148:149], s[20:21], 0, v[134:135]
	s_add_i32 m0, s24, 0x2000
	s_nop 0
	global_load_lds_dwordx4 v[148:149], off
	v_lshl_add_u64 v[148:149], v[218:219], 0, s[6:7]
	s_mov_b32 m0, s37
	s_nop 0
	global_load_lds_dwordx4 v[148:149], off
	v_lshl_add_u64 v[148:149], v[220:221], 0, s[6:7]
	s_mov_b32 m0, s38
	s_nop 0
	global_load_lds_dwordx4 v[148:149], off
	s_nop 0
	s_waitcnt vmcnt(8)
	s_waitcnt lgkmcnt(0)
	s_barrier
	v_mfma_f32_16x16x32_bf16 v[60:63], v[144:147], v[184:187], v[60:63]
	v_mfma_f32_16x16x32_bf16 v[56:59], v[160:163], v[184:187], v[56:59]
	v_mfma_f32_16x16x32_bf16 v[44:47], v[144:147], v[192:195], v[44:47]
	v_mfma_f32_16x16x32_bf16 v[40:43], v[160:163], v[192:195], v[40:43]
	v_mfma_f32_16x16x32_bf16 v[28:31], v[144:147], v[200:203], v[28:31]
	v_mfma_f32_16x16x32_bf16 v[24:27], v[160:163], v[200:203], v[24:27]
	v_mfma_f32_16x16x32_bf16 v[12:15], v[144:147], v[208:211], v[12:15]
	v_mfma_f32_16x16x32_bf16 v[8:11], v[160:163], v[208:211], v[8:11]
	v_mfma_f32_16x16x32_bf16 v[60:63], v[156:159], v[188:191], v[60:63]
	v_mfma_f32_16x16x32_bf16 v[56:59], v[164:167], v[188:191], v[56:59]
	v_mfma_f32_16x16x32_bf16 v[44:47], v[156:159], v[196:199], v[44:47]
	v_mfma_f32_16x16x32_bf16 v[40:43], v[164:167], v[196:199], v[40:43]
	v_mfma_f32_16x16x32_bf16 v[28:31], v[156:159], v[204:207], v[28:31]
	v_mfma_f32_16x16x32_bf16 v[24:27], v[164:167], v[204:207], v[24:27]
	v_mfma_f32_16x16x32_bf16 v[12:15], v[156:159], v[212:215], v[12:15]
	v_mfma_f32_16x16x32_bf16 v[8:11], v[164:167], v[212:215], v[8:11]
	v_mfma_f32_16x16x32_bf16 v[52:55], v[168:171], v[184:187], v[52:55]
	v_mfma_f32_16x16x32_bf16 v[48:51], v[176:179], v[184:187], v[48:51]
	v_mfma_f32_16x16x32_bf16 v[36:39], v[168:171], v[192:195], v[36:39]
	v_mfma_f32_16x16x32_bf16 v[32:35], v[176:179], v[192:195], v[32:35]
	v_mfma_f32_16x16x32_bf16 v[20:23], v[168:171], v[200:203], v[20:23]
	v_mfma_f32_16x16x32_bf16 v[16:19], v[176:179], v[200:203], v[16:19]
	v_mfma_f32_16x16x32_bf16 v[4:7], v[168:171], v[208:211], v[4:7]
	v_mfma_f32_16x16x32_bf16 v[0:3], v[176:179], v[208:211], v[0:3]
	v_mfma_f32_16x16x32_bf16 v[52:55], v[172:175], v[188:191], v[52:55]
	v_mfma_f32_16x16x32_bf16 v[48:51], v[180:183], v[188:191], v[48:51]
	v_mfma_f32_16x16x32_bf16 v[36:39], v[172:175], v[196:199], v[36:39]
	v_mfma_f32_16x16x32_bf16 v[32:35], v[180:183], v[196:199], v[32:35]
	v_mfma_f32_16x16x32_bf16 v[20:23], v[172:175], v[204:207], v[20:23]
	v_mfma_f32_16x16x32_bf16 v[16:19], v[180:183], v[204:207], v[16:19]
	v_mfma_f32_16x16x32_bf16 v[4:7], v[172:175], v[212:215], v[4:7]
	v_mfma_f32_16x16x32_bf16 v[0:3], v[180:183], v[212:215], v[0:3]
	s_barrier
	s_add_i32 s49, s49, 2
	s_add_u32 s47, s47, 0x100
	s_addc_u32 s48, s48, 0
	s_cmpk_gt_u32 s49, 0xa9
	s_mov_b64 s[20:21], s[22:23]
	s_cbranch_scc0 .LBB0_804
	s_and_b64 vcc, exec, s[8:9]
	s_cbranch_vccz .LBB0_807
	s_barrier
